# attention: XOR-swizzled K/V LDS layout (conflict-free b128 fragment reads) + waves 4-7 delayed by s_sleep 5 per tile iteration (stagger)
# baseline (speedup 1.0000x reference)
; DI void attn_item(const Params& p, int item, LAS unsigned char* lds, int tid) {
;     ...
;     const int t0 = tile * 64 + w * 8, tl = i16 >> 2, hh = i16 & 3;
;     constexpr float SC2 = ATT_SCALE * 1.4426950408889634f;
;     bf16x8 q[2][4];
;     unsigned long long msk[2];
; #pragma unroll
;     for (int rt = 0; rt < 2; ++rt) {
;         const int t = t0 + rt * 4 + tl;
;         msk[rt] = sel[t];
;         const bf16_t* qptr = proj + (size_t)(b * T + t) * NINP + C_Q + (g * 4 + hh) * 128 + quad * 8;
;         u32x4 raw[4];
; #pragma unroll
;         for (int kk = 0; kk < 4; ++kk) raw[kk] = *(const u32x4*)(qptr + kk * 32);
; #pragma unroll
;         for (int kk = 0; kk < 2; ++kk) {
;             const int d0 = kk * 32 + quad * 8;
;             const f32x4 c0 = *(const f32x4*)(cosT + t * 64 + d0), c1 = *(const f32x4*)(cosT + t * 64 + d0 + 4);
;             const f32x4 s0 = *(const f32x4*)(sinT + t * 64 + d0), s1 = *(const f32x4*)(sinT + t * 64 + d0 + 4);
;             const u32x4 lo = raw[kk], hi = raw[kk + 2];
;             const float x1[8] = {bflo(lo.x), bfhi(lo.x), bflo(lo.y), bfhi(lo.y), bflo(lo.z), bfhi(lo.z), bflo(lo.w), bfhi(lo.w)};
;             const float x2[8] = {bflo(hi.x), bfhi(hi.x), bflo(hi.y), bfhi(hi.y), bflo(hi.z), bfhi(hi.z), bflo(hi.w), bfhi(hi.w)};
;             const float cc[8] = {c0.x, c0.y, c0.z, c0.w, c1.x, c1.y, c1.z, c1.w}, ss[8] = {s0.x, s0.y, s0.z, s0.w, s1.x, s1.y, s1.z, s1.w};
;             float y1[8], y2[8];
; #pragma unroll
;             for (int e = 0; e < 8; ++e) { y1[e] = (x1[e] * cc[e] - x2[e] * ss[e]) * SC2; y2[e] = (x2[e] * cc[e] + x1[e] * ss[e]) * SC2; }
;             q[rt][kk] = __builtin_bit_cast(bf16x8, (u32x4){pk2(y1[0], y1[1]), pk2(y1[2], y1[3]), pk2(y1[4], y1[5]), pk2(y1[6], y1[7])});
;             q[rt][kk + 2] = __builtin_bit_cast(bf16x8, (u32x4){pk2(y2[0], y2[1]), pk2(y2[2], y2[3]), pk2(y2[4], y2[5]), pk2(y2[6], y2[7])});
;         }
;     }
;     unsigned long long um = sel[tile * 64 + lane];
;     {
;         unsigned ulo = (unsigned)um, uhi = (unsigned)(um >> 32);
; #pragma unroll
;         for (int o = 32; o >= 1; o >>= 1) { ulo |= __shfl_xor(ulo, o); uhi |= __shfl_xor(uhi, o); }
;         ulo = __builtin_amdgcn_readfirstlane(ulo); uhi = __builtin_amdgcn_readfirstlane(uhi);
;         um = ((unsigned long long)uhi << 32) | ulo;
;     }
;     const int kt_hi = tile, kt_lo = tile >= 8 ? tile - 8 : 0;
.LBB0_335:
	s_waitcnt vmcnt(0)
	v_mbcnt_lo_u32_b32 v46, -1, 0
	v_mbcnt_hi_u32_b32 v46, -1, v46
	s_mov_b64 s[6:7], -1
	v_add_u32_e32 v232, s33, v46
	s_cmpk_gt_i32 s2, 0x1ff
	v_and_b32_e32 v233, 63, v46
	v_and_b32_e32 v234, 15, v46
	v_and_b32_e32 v200, 48, v46
	s_cbranch_scc0 .LBB0_388
	s_add_i32 s10, s2, 0xfffffe00
	s_lshr_b32 s4, s10, 4
	s_and_b32 s5, s2, 0x100
	s_xor_b32 s6, s4, 15
	s_cmp_eq_u32 s5, 0
	s_cselect_b32 s56, s4, s6
	s_mov_b64 s[6:7], s[28:29]
	s_and_b32 s4, s2, 1
	s_add_u32 s6, s6, 0x1be00000
	s_addc_u32 s7, s7, 0
	s_mov_b64 s[8:9], s[28:29]
	s_mov_b64 s[12:13], s[28:29]
	s_add_u32 s20, s12, 0x3a080000
	s_addc_u32 s21, s13, 0
	s_mov_b64 s[12:13], s[28:29]
	s_add_u32 s22, s12, 0x3a180000
	s_addc_u32 s23, s13, 0
	s_lshl_b32 s5, s10, 15
	s_mov_b64 s[12:13], s[28:29]
	s_and_b32 s5, s5, 0x78000
	s_add_u32 s5, s12, s5
	s_addc_u32 s13, s13, 0
	s_add_u32 s12, s5, 0x3a000000
	v_ashrrev_i32_e32 v47, 3, v232
	s_addc_u32 s13, s13, 0
	s_lshl_b32 s24, s56, 6
	v_and_b32_e32 v0, -8, v47
	v_add_u32_e32 v113, s24, v0
	v_bfe_u32 v114, v46, 2, 2
	v_or_b32_e32 v202, v113, v114
	v_and_b32_e32 v115, 3, v46
	s_lshl_b32 s25, s4, 10
	v_lshlrev_b32_e32 v16, 6, v202
	s_lshl_b32 s5, s10, 11
	v_lshl_or_b32 v198, v115, 8, s25
	v_ashrrev_i32_e32 v17, 31, v16
	v_bfe_u32 v112, v46, 4, 2
	s_and_b32 s5, s5, 0x7000
	v_lshl_add_u64 v[0:1], s[6:7], 0, v[198:199]
	v_mov_b32_e32 v201, v199
	v_lshlrev_b64 v[16:17], 2, v[16:17]
	v_lshl_add_u64 v[28:29], v[0:1], 0, v[200:201]
	v_ashrrev_i32_e32 v203, 31, v202
	v_add_u32_e32 v0, s5, v202
	v_lshl_add_u64 v[18:19], s[20:21], 0, v[16:17]
	v_lshl_add_u64 v[24:25], s[22:23], 0, v[16:17]
	v_lshlrev_b32_e32 v32, 5, v112
	v_mov_b32_e32 v33, v199
	v_lshl_add_u64 v[30:31], v[202:203], 3, s[12:13]
	v_mad_i64_i32 v[12:13], s[48:49], v0, s96, v[28:29]
	v_lshl_add_u64 v[40:41], v[18:19], 0, v[32:33]
	v_lshl_add_u64 v[34:35], v[24:25], 0, v[32:33]
	global_load_dwordx2 v[204:205], v[30:31], off
	global_load_dwordx4 v[0:3], v[12:13], off
	global_load_dwordx4 v[8:11], v[12:13], off offset:64
	global_load_dwordx4 v[4:7], v[12:13], off offset:128
	s_nop 0
	global_load_dwordx4 v[12:15], v[12:13], off offset:192
	s_nop 0
	global_load_dwordx4 v[16:19], v[40:41], off offset:16
	global_load_dwordx4 v[20:23], v[40:41], off
	global_load_dwordx4 v[24:27], v[34:35], off offset:16
	global_load_dwordx4 v[36:39], v[34:35], off
	v_or_b32_e32 v201, 4, v202
	s_lshl_b32 s10, s10, 1
	v_lshlrev_b32_e32 v121, 4, v46
	s_and_b32 s10, s10, 28
	s_lshl_b32 s84, s4, 8
	s_or_b32 s10, s10, s4
	s_add_i32 s57, s56, -8
	v_ashrrev_i32_e32 v120, 2, v232
	v_mov_b32_e32 v209, v199
	v_add_u32_e32 v229, 4, v234
	v_lshlrev_b32_e32 v229, 1, v229
	v_and_b32_e32 v229, 16, v229
	v_xor_b32_e32 v229, v229, v200
	v_ashrrev_i32_e32 v230, 3, v232
	v_add_u32_e32 v230, 4, v230
	v_lshlrev_b32_e32 v230, 1, v230
	v_and_b32_e32 v230, 16, v230
	v_add_u32_e32 v228, 4, v120
	v_lshlrev_b32_e32 v228, 1, v228
	v_and_b32_e32 v228, 16, v228
	s_lshl_b32 s10, s10, 20
	s_mov_b32 s11, 0
	v_lshlrev_b32_e32 v198, 3, v112
	v_lshlrev_b32_e32 v241, 2, v112
	v_add_u32_e32 v112, s5, v113
	v_lshl_or_b32 v113, s4, 2, v115
	v_or_b32_e32 v112, v112, v114
	v_mul_u32_u24_e32 v114, 3, v113
	v_lshlrev_b32_e32 v114, 1, v114
	v_mul_u32_u24_e32 v237, 0x110, v234
	v_mul_u32_u24_e32 v238, 0x90, v234
	v_add_u32_e32 v240, 0xfffffe04, v202
	v_add_u32_e32 v242, 0xfffffe00, v202
	v_mov_b32_e32 v244, 0xc61c4000
	v_mov_b32_e32 v245, 0xc61c4000
	v_mov_b32_e32 v243, 0
	s_waitcnt vmcnt(0)
	v_lshlrev_b32_e32 v42, 16, v0
	v_and_b32_e32 v43, 0xffff0000, v0
	s_waitcnt vmcnt(5)
	v_lshlrev_b32_e32 v44, 16, v4
	v_and_b32_e32 v45, 0xffff0000, v4
	v_lshlrev_b32_e32 v4, 16, v5
	s_waitcnt vmcnt(0)
	v_pk_mul_f32 v[48:49], v[36:37], v[44:45]
	v_pk_mul_f32 v[36:37], v[36:37], v[42:43]
	v_and_b32_e32 v5, 0xffff0000, v5
	v_pk_fma_f32 v[48:49], v[20:21], v[42:43], v[48:49] neg_lo:[0,0,1] neg_hi:[0,0,1]
	v_pk_fma_f32 v[20:21], v[20:21], v[44:45], v[36:37]
	v_lshlrev_b32_e32 v0, 16, v1
	v_and_b32_e32 v1, 0xffff0000, v1
	v_pk_mul_f32 v[36:37], v[38:39], v[4:5]
	v_pk_mul_f32 v[20:21], v[20:21], s[64:65] op_sel_hi:[1,0]
	v_pk_fma_f32 v[36:37], v[22:23], v[0:1], v[36:37] neg_lo:[0,0,1] neg_hi:[0,0,1]
	v_pk_mul_f32 v[0:1], v[38:39], v[0:1]
	v_pk_mul_f32 v[36:37], v[36:37], s[64:65] op_sel_hi:[1,0]
	v_pk_fma_f32 v[0:1], v[22:23], v[4:5], v[0:1]
	v_lshlrev_b32_e32 v4, 16, v6
	v_and_b32_e32 v5, 0xffff0000, v6
	v_pk_mul_f32 v[22:23], v[0:1], s[64:65] op_sel_hi:[1,0]
	v_lshlrev_b32_e32 v0, 16, v2
	v_and_b32_e32 v1, 0xffff0000, v2
	v_pk_mul_f32 v[38:39], v[24:25], v[4:5]
	v_lshlrev_b32_e32 v2, 16, v7
	v_pk_fma_f32 v[38:39], v[16:17], v[0:1], v[38:39] neg_lo:[0,0,1] neg_hi:[0,0,1]
	v_pk_mul_f32 v[0:1], v[24:25], v[0:1]
	v_pk_mul_f32 v[38:39], v[38:39], s[64:65] op_sel_hi:[1,0]
	v_pk_fma_f32 v[0:1], v[16:17], v[4:5], v[0:1]
	v_pk_mul_f32 v[48:49], v[48:49], s[64:65] op_sel_hi:[1,0]
	v_pk_mul_f32 v[16:17], v[0:1], s[64:65] op_sel_hi:[1,0]
	v_lshlrev_b32_e32 v0, 16, v3
	v_and_b32_e32 v1, 0xffff0000, v3
	v_and_b32_e32 v3, 0xffff0000, v7
	v_pk_mul_f32 v[4:5], v[26:27], v[2:3]
	v_cvt_pk_bf16_f32 v6, v16, v17
	v_pk_fma_f32 v[4:5], v[18:19], v[0:1], v[4:5] neg_lo:[0,0,1] neg_hi:[0,0,1]
	v_pk_mul_f32 v[0:1], v[26:27], v[0:1]
	v_pk_mul_f32 v[4:5], v[4:5], s[64:65] op_sel_hi:[1,0]
	v_pk_fma_f32 v[0:1], v[18:19], v[2:3], v[0:1]
	v_cvt_pk_bf16_f32 v3, v4, v5
	v_pk_mul_f32 v[18:19], v[0:1], s[64:65] op_sel_hi:[1,0]
	v_cvt_pk_bf16_f32 v1, v36, v37
	v_cvt_pk_bf16_f32 v4, v20, v21
	v_cvt_pk_bf16_f32 v5, v22, v23
	v_cvt_pk_bf16_f32 v7, v18, v19
	global_load_dwordx4 v[16:19], v[40:41], off offset:144
	global_load_dwordx4 v[24:27], v[40:41], off offset:128
	global_load_dwordx4 v[20:23], v[34:35], off offset:144
	s_nop 0
	global_load_dwordx4 v[34:37], v[34:35], off offset:128
	v_cvt_pk_bf16_f32 v2, v38, v39
	v_lshlrev_b32_e32 v38, 16, v8
	v_and_b32_e32 v39, 0xffff0000, v8
	v_lshlrev_b32_e32 v40, 16, v12
	v_and_b32_e32 v41, 0xffff0000, v12
	v_lshlrev_b32_e32 v12, 16, v13
	v_and_b32_e32 v13, 0xffff0000, v13
	v_lshlrev_b32_e32 v8, 16, v9
	v_and_b32_e32 v9, 0xffff0000, v9
	v_cvt_pk_bf16_f32 v0, v48, v49
	global_load_dwordx2 v[206:207], v[30:31], off offset:32
	s_waitcnt vmcnt(0)
; DI unsigned pk2(float lo, float hi) { f32x2 v = {lo, hi}; bf16v2 b = __builtin_convertvector(v, bf16v2); return __builtin_bit_cast(unsigned, b); }
; DI float bflo(unsigned v) { return __uint_as_float(v << 16); }
; DI float bfhi(unsigned v) { return __uint_as_float(v & 0xffff0000u); }
; DI void attn_item(const Params& p, int item, LAS unsigned char* lds, int tid) {
;     ...
;     for (int rt = 0; rt < 2; ++rt) {
;         const int t = t0 + rt * 4 + tl;
;         msk[rt] = sel[t];
;         const bf16_t* qptr = proj + (size_t)(b * T + t) * NINP + C_Q + (g * 4 + hh) * 128 + quad * 8;
;         u32x4 raw[4];
; #pragma unroll
;         for (int kk = 0; kk < 4; ++kk) raw[kk] = *(const u32x4*)(qptr + kk * 32);
; #pragma unroll
;         for (int kk = 0; kk < 2; ++kk) {
;             const int d0 = kk * 32 + quad * 8;
;             const f32x4 c0 = *(const f32x4*)(cosT + t * 64 + d0), c1 = *(const f32x4*)(cosT + t * 64 + d0 + 4);
;             const f32x4 s0 = *(const f32x4*)(sinT + t * 64 + d0), s1 = *(const f32x4*)(sinT + t * 64 + d0 + 4);
;             const u32x4 lo = raw[kk], hi = raw[kk + 2];
;             const float x1[8] = {bflo(lo.x), bfhi(lo.x), bflo(lo.y), bfhi(lo.y), bflo(lo.z), bfhi(lo.z), bflo(lo.w), bfhi(lo.w)};
;             const float x2[8] = {bflo(hi.x), bfhi(hi.x), bflo(hi.y), bfhi(hi.y), bflo(hi.z), bfhi(hi.z), bflo(hi.w), bfhi(hi.w)};
;             const float cc[8] = {c0.x, c0.y, c0.z, c0.w, c1.x, c1.y, c1.z, c1.w}, ss[8] = {s0.x, s0.y, s0.z, s0.w, s1.x, s1.y, s1.z, s1.w};
;             float y1[8], y2[8];
; #pragma unroll
;             for (int e = 0; e < 8; ++e) { y1[e] = (x1[e] * cc[e] - x2[e] * ss[e]) * SC2; y2[e] = (x2[e] * cc[e] + x1[e] * ss[e]) * SC2; }
;             q[rt][kk] = __builtin_bit_cast(bf16x8, (u32x4){pk2(y1[0], y1[1]), pk2(y1[2], y1[3]), pk2(y1[4], y1[5]), pk2(y1[6], y1[7])});
;             q[rt][kk + 2] = __builtin_bit_cast(bf16x8, (u32x4){pk2(y2[0], y2[1]), pk2(y2[2], y2[3]), pk2(y2[4], y2[5]), pk2(y2[6], y2[7])});
;         }
	v_pk_mul_f32 v[42:43], v[34:35], v[40:41]
	v_pk_mul_f32 v[34:35], v[34:35], v[38:39]
	v_pk_fma_f32 v[42:43], v[24:25], v[38:39], v[42:43] neg_lo:[0,0,1] neg_hi:[0,0,1]
	v_pk_fma_f32 v[24:25], v[24:25], v[40:41], v[34:35]
	v_pk_mul_f32 v[34:35], v[36:37], v[12:13]
	v_pk_mul_f32 v[42:43], v[42:43], s[64:65] op_sel_hi:[1,0]
	v_pk_fma_f32 v[34:35], v[26:27], v[8:9], v[34:35] neg_lo:[0,0,1] neg_hi:[0,0,1]
	v_pk_mul_f32 v[8:9], v[36:37], v[8:9]
	v_pk_mul_f32 v[34:35], v[34:35], s[64:65] op_sel_hi:[1,0]
	v_pk_fma_f32 v[8:9], v[26:27], v[12:13], v[8:9]
	v_lshlrev_b32_e32 v12, 16, v14
	v_and_b32_e32 v13, 0xffff0000, v14
	v_pk_mul_f32 v[26:27], v[8:9], s[64:65] op_sel_hi:[1,0]
	v_lshlrev_b32_e32 v8, 16, v10
	v_and_b32_e32 v9, 0xffff0000, v10
	v_pk_mul_f32 v[36:37], v[20:21], v[12:13]
	v_lshlrev_b32_e32 v10, 16, v15
	v_pk_fma_f32 v[36:37], v[16:17], v[8:9], v[36:37] neg_lo:[0,0,1] neg_hi:[0,0,1]
	v_pk_mul_f32 v[8:9], v[20:21], v[8:9]
	v_pk_mul_f32 v[36:37], v[36:37], s[64:65] op_sel_hi:[1,0]
	v_pk_fma_f32 v[8:9], v[16:17], v[12:13], v[8:9]
	v_pk_mul_f32 v[24:25], v[24:25], s[64:65] op_sel_hi:[1,0]
	v_pk_mul_f32 v[16:17], v[8:9], s[64:65] op_sel_hi:[1,0]
	v_lshlrev_b32_e32 v8, 16, v11
	v_and_b32_e32 v9, 0xffff0000, v11
	v_and_b32_e32 v11, 0xffff0000, v15
	v_pk_mul_f32 v[12:13], v[22:23], v[10:11]
	v_cvt_pk_bf16_f32 v14, v16, v17
	v_pk_fma_f32 v[12:13], v[18:19], v[8:9], v[12:13] neg_lo:[0,0,1] neg_hi:[0,0,1]
	v_pk_mul_f32 v[8:9], v[22:23], v[8:9]
	v_add_u32_e32 v16, s5, v201
	v_pk_fma_f32 v[8:9], v[18:19], v[10:11], v[8:9]
	v_cvt_pk_bf16_f32 v10, v36, v37
	v_pk_mul_f32 v[18:19], v[8:9], s[64:65] op_sel_hi:[1,0]
	v_cvt_pk_bf16_f32 v9, v34, v35
	v_lshlrev_b32_e32 v34, 6, v201
	v_ashrrev_i32_e32 v35, 31, v34
	v_lshlrev_b64 v[34:35], 2, v[34:35]
	v_cvt_pk_bf16_f32 v8, v42, v43
	v_lshl_add_u64 v[36:37], s[20:21], 0, v[34:35]
	v_lshl_add_u64 v[42:43], s[22:23], 0, v[34:35]
	v_pk_mul_f32 v[12:13], v[12:13], s[64:65] op_sel_hi:[1,0]
	v_mad_i64_i32 v[28:29], s[48:49], v16, s96, v[28:29]
	v_lshl_add_u64 v[56:57], v[36:37], 0, v[32:33]
	v_lshl_add_u64 v[44:45], v[42:43], 0, v[32:33]
	v_cvt_pk_bf16_f32 v11, v12, v13
	v_cvt_pk_bf16_f32 v12, v24, v25
	v_cvt_pk_bf16_f32 v13, v26, v27
	v_cvt_pk_bf16_f32 v15, v18, v19
	global_load_dwordx4 v[16:19], v[28:29], off
	global_load_dwordx4 v[24:27], v[28:29], off offset:64
	global_load_dwordx4 v[20:23], v[28:29], off offset:128
	s_nop 0
	global_load_dwordx4 v[28:31], v[28:29], off offset:192
	s_nop 0
	global_load_dwordx4 v[34:37], v[56:57], off offset:16
	global_load_dwordx4 v[38:41], v[56:57], off
	global_load_dwordx4 v[48:51], v[44:45], off offset:16
	global_load_dwordx4 v[52:55], v[44:45], off
	s_waitcnt vmcnt(0)
	v_lshlrev_b32_e32 v32, 16, v16
	v_and_b32_e32 v33, 0xffff0000, v16
	s_waitcnt vmcnt(5)
	v_lshlrev_b32_e32 v42, 16, v20
	v_and_b32_e32 v43, 0xffff0000, v20
	v_lshlrev_b32_e32 v20, 16, v21
	s_waitcnt vmcnt(0)
	v_pk_mul_f32 v[58:59], v[52:53], v[42:43]
	v_and_b32_e32 v21, 0xffff0000, v21
	v_pk_fma_f32 v[58:59], v[38:39], v[32:33], v[58:59] neg_lo:[0,0,1] neg_hi:[0,0,1]
	v_pk_mul_f32 v[32:33], v[52:53], v[32:33]
	v_lshlrev_b32_e32 v16, 16, v17
	v_pk_fma_f32 v[32:33], v[38:39], v[42:43], v[32:33]
	v_and_b32_e32 v17, 0xffff0000, v17
	v_pk_mul_f32 v[38:39], v[54:55], v[20:21]
	v_pk_mul_f32 v[32:33], v[32:33], s[64:65] op_sel_hi:[1,0]
	v_pk_fma_f32 v[38:39], v[40:41], v[16:17], v[38:39] neg_lo:[0,0,1] neg_hi:[0,0,1]
	v_pk_mul_f32 v[16:17], v[54:55], v[16:17]
	v_pk_mul_f32 v[38:39], v[38:39], s[64:65] op_sel_hi:[1,0]
	v_pk_fma_f32 v[16:17], v[40:41], v[20:21], v[16:17]
	v_lshlrev_b32_e32 v20, 16, v22
	v_and_b32_e32 v21, 0xffff0000, v22
	v_pk_mul_f32 v[40:41], v[16:17], s[64:65] op_sel_hi:[1,0]
	v_lshlrev_b32_e32 v16, 16, v18
	v_and_b32_e32 v17, 0xffff0000, v18
	v_pk_mul_f32 v[42:43], v[48:49], v[20:21]
	v_lshlrev_b32_e32 v18, 16, v23
	v_pk_fma_f32 v[42:43], v[34:35], v[16:17], v[42:43] neg_lo:[0,0,1] neg_hi:[0,0,1]
	v_pk_mul_f32 v[16:17], v[48:49], v[16:17]
	v_pk_mul_f32 v[42:43], v[42:43], s[64:65] op_sel_hi:[1,0]
	v_pk_fma_f32 v[16:17], v[34:35], v[20:21], v[16:17]
	v_lshlrev_b32_e32 v52, 16, v28
	v_pk_mul_f32 v[34:35], v[16:17], s[64:65] op_sel_hi:[1,0]
	v_lshlrev_b32_e32 v16, 16, v19
	v_and_b32_e32 v17, 0xffff0000, v19
	v_and_b32_e32 v19, 0xffff0000, v23
	v_pk_mul_f32 v[20:21], v[50:51], v[18:19]
	v_cvt_pk_bf16_f32 v22, v34, v35
	v_pk_fma_f32 v[20:21], v[36:37], v[16:17], v[20:21] neg_lo:[0,0,1] neg_hi:[0,0,1]
	v_pk_mul_f32 v[16:17], v[50:51], v[16:17]
	v_pk_mul_f32 v[20:21], v[20:21], s[64:65] op_sel_hi:[1,0]
	v_pk_fma_f32 v[16:17], v[36:37], v[18:19], v[16:17]
	v_cvt_pk_bf16_f32 v18, v42, v43
	v_pk_mul_f32 v[36:37], v[16:17], s[64:65] op_sel_hi:[1,0]
	v_cvt_pk_bf16_f32 v17, v38, v39
	v_cvt_pk_bf16_f32 v19, v20, v21
	v_cvt_pk_bf16_f32 v20, v32, v33
	v_cvt_pk_bf16_f32 v21, v40, v41
	v_cvt_pk_bf16_f32 v23, v36, v37
	global_load_dwordx4 v[32:35], v[56:57], off offset:144
	global_load_dwordx4 v[36:39], v[56:57], off offset:128
	global_load_dwordx4 v[40:43], v[44:45], off offset:144
	global_load_dwordx4 v[48:51], v[44:45], off offset:128
	v_and_b32_e32 v53, 0xffff0000, v28
	v_lshlrev_b32_e32 v44, 16, v24
	v_and_b32_e32 v45, 0xffff0000, v24
	v_lshlrev_b32_e32 v28, 16, v29
	v_and_b32_e32 v29, 0xffff0000, v29
	v_lshlrev_b32_e32 v24, 16, v25
	v_and_b32_e32 v25, 0xffff0000, v25
	v_pk_mul_f32 v[58:59], v[58:59], s[64:65] op_sel_hi:[1,0]
	s_waitcnt vmcnt(0)
; DI f32x4 zero4() { float a, b, c, d; asm volatile("v_mov_b32 %0, 0\n\tv_mov_b32 %1, 0\n\tv_mov_b32 %2, 0\n\tv_mov_b32 %3, 0\n\ts_nop 1" : "=v"(a), "=v"(b), "=v"(c), "=v"(d)); return (f32x4){a, b, c, d}; }
; DI unsigned char* WSP(const Params& p) { GAS unsigned char* w = (GAS unsigned char*)p.ws; asm volatile("" : "+s"(w)); return (unsigned char*)w; }
; #define ATT_PREFETCH(BR, KT) do { const bf16_t* ks_ = kb0 + (size_t)(KT) * 64 * NINP + ((BR) ? C_KW : C_KS); const bf16_t* vs_ = vb0 + (size_t)(BR) * 2 * 64 * 8192 + (size_t)(KT) * 8192; \
;         pk0 = *(const u32x4*)ks_; pk1 = *(const u32x4*)(ks_ + 8); pv0 = *(const u32x4*)vs_; pv1 = *(const u32x4*)(vs_ + 8); } while (0)
; DI void attn_item(const Params& p, int item, LAS unsigned char* lds, int tid) {
;     ...
;     unsigned long long um = sel[tile * 64 + lane];
;     {
;         unsigned ulo = (unsigned)um, uhi = (unsigned)(um >> 32);
; #pragma unroll
;         for (int o = 32; o >= 1; o >>= 1) { ulo |= __shfl_xor(ulo, o); uhi |= __shfl_xor(uhi, o); }
;         ulo = __builtin_amdgcn_readfirstlane(ulo); uhi = __builtin_amdgcn_readfirstlane(uhi);
;         um = ((unsigned long long)uhi << 32) | ulo;
;     }
;     const int kt_hi = tile, kt_lo = tile >= 8 ? tile - 8 : 0;
;     const int skey = tid >> 3, sch = tid & 7, sdd = tid >> 2, sc4 = tid & 3;
;     const bf16_t* kb0 = proj + (size_t)(b * T + skey) * NINP + g * 128 + sch * 16;
;     const bf16_t* vb0 = (const bf16_t*)(WSP(p) + WS_VT) + (size_t)(b * 2 * 2 + g) * 64 * 8192 + sdd * 64 + sc4 * 16;
;     u32x4 pk0, pk1, pv0, pv1;
;     ...
;     unsigned long long rem = um;
;     int br = 0, kt = __builtin_ctzll(rem); rem &= rem - 1;
;     ATT_PREFETCH(br, kt);
;     float m[2] = {-1e4f, -1e4f}, l[2] = {0.f, 0.f};
;     f32x4 O[2][8];
; #pragma unroll
;     for (int rt = 0; rt < 2; ++rt)
; #pragma unroll
;         for (int dt = 0; dt < 8; ++dt) O[rt][dt] = zero4();
	v_pk_mul_f32 v[54:55], v[48:49], v[52:53]
	s_nop 0
	v_pk_fma_f32 v[54:55], v[36:37], v[44:45], v[54:55] neg_lo:[0,0,1] neg_hi:[0,0,1]
	v_pk_mul_f32 v[44:45], v[48:49], v[44:45]
	v_pk_mul_f32 v[54:55], v[54:55], s[64:65] op_sel_hi:[1,0]
	v_pk_fma_f32 v[36:37], v[36:37], v[52:53], v[44:45]
	v_pk_mul_f32 v[44:45], v[50:51], v[28:29]
	v_pk_mul_f32 v[36:37], v[36:37], s[64:65] op_sel_hi:[1,0]
	v_pk_fma_f32 v[44:45], v[38:39], v[24:25], v[44:45] neg_lo:[0,0,1] neg_hi:[0,0,1]
	v_pk_mul_f32 v[24:25], v[50:51], v[24:25]
	v_pk_mul_f32 v[44:45], v[44:45], s[64:65] op_sel_hi:[1,0]
	v_pk_fma_f32 v[24:25], v[38:39], v[28:29], v[24:25]
	v_lshlrev_b32_e32 v28, 16, v30
	v_and_b32_e32 v29, 0xffff0000, v30
	v_pk_mul_f32 v[38:39], v[24:25], s[64:65] op_sel_hi:[1,0]
	v_lshlrev_b32_e32 v24, 16, v26
	v_and_b32_e32 v25, 0xffff0000, v26
	v_pk_mul_f32 v[48:49], v[40:41], v[28:29]
	v_lshlrev_b32_e32 v26, 16, v31
	v_pk_fma_f32 v[48:49], v[32:33], v[24:25], v[48:49] neg_lo:[0,0,1] neg_hi:[0,0,1]
	v_pk_mul_f32 v[24:25], v[40:41], v[24:25]
	v_pk_mul_f32 v[48:49], v[48:49], s[64:65] op_sel_hi:[1,0]
	v_pk_fma_f32 v[24:25], v[32:33], v[28:29], v[24:25]
	v_cvt_pk_bf16_f32 v16, v58, v59
	v_pk_mul_f32 v[32:33], v[24:25], s[64:65] op_sel_hi:[1,0]
	v_lshlrev_b32_e32 v24, 16, v27
	v_cvt_pk_bf16_f32 v30, v32, v33
	v_or_b32_e32 v32, s24, v233
	v_mov_b32_e32 v33, v199
	v_lshl_add_u64 v[32:33], v[32:33], 3, s[12:13]
	global_load_dwordx2 v[32:33], v[32:33], off
	v_and_b32_e32 v25, 0xffff0000, v27
	v_and_b32_e32 v27, 0xffff0000, v31
	v_pk_mul_f32 v[28:29], v[42:43], v[26:27]
	s_nop 0
	v_pk_fma_f32 v[28:29], v[34:35], v[24:25], v[28:29] neg_lo:[0,0,1] neg_hi:[0,0,1]
	v_pk_mul_f32 v[24:25], v[42:43], v[24:25]
	v_pk_mul_f32 v[28:29], v[28:29], s[64:65] op_sel_hi:[1,0]
	v_pk_fma_f32 v[24:25], v[34:35], v[26:27], v[24:25]
	v_cvt_pk_bf16_f32 v27, v28, v29
	v_pk_mul_f32 v[34:35], v[24:25], s[64:65] op_sel_hi:[1,0]
	v_cvt_pk_bf16_f32 v28, v36, v37
	v_cvt_pk_bf16_f32 v31, v34, v35
	v_and_b32_e32 v34, 64, v227
	v_add_u32_e32 v34, 64, v34
	v_xor_b32_e32 v35, 32, v227
	v_cmp_lt_i32_e32 vcc, v35, v34
	v_cvt_pk_bf16_f32 v25, v44, v45
	v_cvt_pk_bf16_f32 v29, v38, v39
	v_cndmask_b32_e32 v35, v227, v35, vcc
	v_lshlrev_b32_e32 v35, 2, v35
	v_cvt_pk_bf16_f32 v24, v54, v55
	v_cvt_pk_bf16_f32 v26, v48, v49
	s_waitcnt vmcnt(0)
	ds_bpermute_b32 v36, v35, v32
	ds_bpermute_b32 v35, v35, v33
	s_waitcnt lgkmcnt(0)
	v_or_b32_e32 v32, v36, v32
	s_waitcnt lgkmcnt(0)
	v_or_b32_e32 v33, v35, v33
	v_xor_b32_e32 v35, 16, v227
	v_cmp_lt_i32_e32 vcc, v35, v34
	s_nop 1
	v_cndmask_b32_e32 v35, v227, v35, vcc
	v_lshlrev_b32_e32 v35, 2, v35
	ds_bpermute_b32 v36, v35, v32
	ds_bpermute_b32 v35, v35, v33
	s_waitcnt lgkmcnt(1)
	v_or_b32_e32 v32, v36, v32
	s_waitcnt lgkmcnt(0)
	v_or_b32_e32 v33, v35, v33
	v_xor_b32_e32 v35, 8, v227
	v_cmp_lt_i32_e32 vcc, v35, v34
	s_nop 1
	v_cndmask_b32_e32 v35, v227, v35, vcc
	v_lshlrev_b32_e32 v35, 2, v35
	ds_bpermute_b32 v36, v35, v32
	ds_bpermute_b32 v35, v35, v33
	s_waitcnt lgkmcnt(1)
	v_or_b32_e32 v32, v36, v32
	s_waitcnt lgkmcnt(0)
	v_or_b32_e32 v33, v35, v33
	v_xor_b32_e32 v35, 4, v227
	v_cmp_lt_i32_e32 vcc, v35, v34
	s_nop 1
	v_cndmask_b32_e32 v35, v227, v35, vcc
	v_lshlrev_b32_e32 v35, 2, v35
	ds_bpermute_b32 v36, v35, v32
	ds_bpermute_b32 v35, v35, v33
	s_waitcnt lgkmcnt(1)
	v_or_b32_e32 v32, v36, v32
	s_waitcnt lgkmcnt(0)
	v_or_b32_e32 v33, v35, v33
	v_xor_b32_e32 v35, 2, v227
	v_cmp_lt_i32_e32 vcc, v35, v34
	s_nop 1
	v_cndmask_b32_e32 v35, v227, v35, vcc
	v_lshlrev_b32_e32 v35, 2, v35
	ds_bpermute_b32 v36, v35, v32
	ds_bpermute_b32 v35, v35, v33
	s_waitcnt lgkmcnt(1)
	v_or_b32_e32 v32, v36, v32
	s_waitcnt lgkmcnt(0)
	v_or_b32_e32 v33, v35, v33
	v_xor_b32_e32 v35, 1, v227
	v_cmp_lt_i32_e32 vcc, v35, v34
	s_nop 1
	v_cndmask_b32_e32 v34, v227, v35, vcc
	v_lshlrev_b32_e32 v34, 2, v34
	ds_bpermute_b32 v35, v34, v32
	ds_bpermute_b32 v34, v34, v33
	s_waitcnt lgkmcnt(1)
	v_or_b32_e32 v32, v35, v32
	s_waitcnt lgkmcnt(0)
	v_or_b32_e32 v33, v34, v33
	v_readfirstlane_b32 s12, v32
	v_readfirstlane_b32 s13, v33
	v_add_u32_e32 v34, s5, v47
	v_mov_b64_e32 v[32:33], s[6:7]
	v_mad_i64_i32 v[32:33], s[20:21], v34, s96, v[32:33]
	v_and_b32_e32 v34, 0x70, v121
	s_mov_b64 s[20:21], s[28:29]
	v_lshl_add_u64 v[32:33], v[32:33], 0, s[84:85]
	v_lshlrev_b32_e32 v208, 1, v34
	v_lshl_add_u64 v[210:211], v[32:33], 0, v[208:209]
	s_add_u32 s20, s20, s10
	v_lshlrev_b32_e32 v32, 6, v120
	s_addc_u32 s21, s21, 0
	v_ashrrev_i32_e32 v33, 31, v32
	v_lshl_add_u64 v[32:33], v[32:33], 1, s[20:21]
	v_lshlrev_b32_e32 v34, 5, v115
	v_mov_b32_e32 v35, v199
	v_lshl_add_u64 v[32:33], v[32:33], 0, v[34:35]
	s_mov_b64 s[20:21], 0x35e00000
	s_ff1_i32_b64 s54, s[12:13]
	v_lshl_add_u64 v[212:213], v[32:33], 0, s[20:21]
	s_add_u32 s20, s12, -1
	s_mul_i32 s84, s54, 0x98000
	s_addc_u32 s21, s13, -1
	v_lshl_add_u64 v[36:37], v[210:211], 0, s[84:85]
	s_lshl_b32 s84, s54, 14
	v_lshl_add_u64 v[44:45], v[212:213], 0, s[84:85]
	global_load_dwordx4 v[32:35], v[36:37], off offset:3088
	s_nop 0
	global_load_dwordx4 v[36:39], v[36:37], off offset:3072
	s_nop 0
	global_load_dwordx4 v[40:43], v[44:45], off offset:16
	global_load_dwordx4 v[116:119], v[44:45], off
	s_movk_i32 s10, 0x88
	v_mul_lo_u32 v44, v47, s10
	v_lshlrev_b32_e32 v203, 1, v44
	s_cmp_gt_u32 s56, 7
	v_add3_u32 v44, 0, v203, v208
	v_mov_b32 v76, 0
	v_mov_b32 v77, 0
	v_mov_b32 v78, 0
	v_mov_b32 v79, 0
	s_nop 1
	v_mov_b32 v72, 0
	v_mov_b32 v73, 0
	v_mov_b32 v74, 0
	v_mov_b32 v75, 0
	s_nop 1
	v_mov_b32 v68, 0
	v_mov_b32 v69, 0
	v_mov_b32 v70, 0
	v_mov_b32 v71, 0
	s_nop 1
	v_mov_b32 v60, 0
	v_mov_b32 v61, 0
	v_mov_b32 v62, 0
	v_mov_b32 v63, 0
	s_nop 1
	v_mov_b32 v48, 0
	v_mov_b32 v49, 0
	v_mov_b32 v50, 0
	v_mov_b32 v51, 0
	s_nop 1
	v_mov_b32 v52, 0
	v_mov_b32 v53, 0
	v_mov_b32 v54, 0
	v_mov_b32 v55, 0
	s_nop 1
	v_mov_b32 v56, 0
	v_mov_b32 v57, 0
	v_mov_b32 v58, 0
	v_mov_b32 v59, 0
	s_nop 1
	v_mov_b32 v64, 0
	v_mov_b32 v65, 0
	v_mov_b32 v66, 0
	v_mov_b32 v67, 0
	s_nop 1
	v_mov_b32 v80, 0
	v_mov_b32 v81, 0
	v_mov_b32 v82, 0
	v_mov_b32 v83, 0
	s_nop 1
	v_mov_b32 v84, 0
	v_mov_b32 v85, 0
	v_mov_b32 v86, 0
	v_mov_b32 v87, 0
	s_nop 1
	v_mov_b32 v88, 0
	v_mov_b32 v89, 0
	v_mov_b32 v90, 0
	v_mov_b32 v91, 0
	s_nop 1
	v_mov_b32 v92, 0
	v_mov_b32 v93, 0
	v_mov_b32 v94, 0
	v_mov_b32 v95, 0
	s_nop 1
	v_mov_b32 v96, 0
	v_mov_b32 v97, 0
	v_mov_b32 v98, 0
	v_mov_b32 v99, 0
	s_nop 1
	v_mov_b32 v100, 0
	v_mov_b32 v101, 0
	v_mov_b32 v102, 0
	v_mov_b32 v103, 0
	s_nop 1
	v_mov_b32 v104, 0
	v_mov_b32 v105, 0
	v_mov_b32 v106, 0
	v_mov_b32 v107, 0
	s_nop 1
	v_mov_b32 v108, 0
	v_mov_b32 v109, 0
	v_mov_b32 v110, 0
	v_mov_b32 v111, 0
	s_nop 1
	s_cselect_b32 s60, s57, 0
	s_and_b64 s[12:13], s[20:21], s[12:13]
	s_barrier
; #define LAS __attribute__((address_space(3)))
; #define ATT_PREFETCH(BR, KT) do { const bf16_t* ks_ = kb0 + (size_t)(KT) * 64 * NINP + ((BR) ? C_KW : C_KS); const bf16_t* vs_ = vb0 + (size_t)(BR) * 2 * 64 * 8192 + (size_t)(KT) * 8192; \
;         pk0 = *(const u32x4*)ks_; pk1 = *(const u32x4*)(ks_ + 8); pv0 = *(const u32x4*)vs_; pv1 = *(const u32x4*)(vs_ + 8); } while (0)
; DI void attn_item(const Params& p, int item, LAS unsigned char* lds, int tid) {
;     ...
;     int nbr = br, nkt = kt + 1; bool has_next = true;
;     {
;         LAS bf16_t* Kl = KV0; LAS bf16_t* Vl = KV0 + 64 * 136;
;         __syncthreads();
;         *(LAS u32x4*)(Kl + skey * 136 + sch * 16) = pk0; *(LAS u32x4*)(Kl + skey * 136 + sch * 16 + 8) = pk1;
;         { LAS bf16_t* vr_ = Vl + sdd * 72 + (sc4 >> 1) * 32 + (sc4 & 1) * 4;     *(LAS u32x2*)(vr_) = (u32x2){pv0.x, pv0.y}; *(LAS u32x2*)(vr_ + 8) = (u32x2){pv0.z, pv0.w}; *(LAS u32x2*)(vr_ + 16) = (u32x2){pv1.x, pv1.y}; *(LAS u32x2*)(vr_ + 24) = (u32x2){pv1.z, pv1.w}; }
;         if (rem) { nkt = __builtin_ctzll(rem); rem &= rem - 1; } else { nbr = 1; nkt = kt_lo; }
;         ATT_PREFETCH(nbr, nkt);
;         __syncthreads();
;     }
	v_add_u32_e32 v122, v230, v44
	v_sub_u32_e32 v123, v44, v230
	s_waitcnt vmcnt(2)
	ds_write_b128 v122, v[36:39]
	ds_write_b128 v123, v[32:35] offset:16
	v_and_b32_e32 v33, 32, v121
	s_movk_i32 s10, 0x48
	v_lshlrev_b32_e32 v235, 1, v33
	v_lshlrev_b32_e32 v33, 2, v46
	s_cmp_eq_u64 s[12:13], 0
	v_mul_lo_u32 v209, v120, s10
	v_and_b32_e32 v33, 4, v33
	s_cselect_b64 s[20:21], -1, 0
	s_add_u32 s22, s12, -1
	v_lshl_add_u32 v32, v209, 1, 0
	v_lshlrev_b32_e32 v236, 1, v33
	s_addc_u32 s23, s13, -1
	v_add3_u32 v32, v32, v235, v236
	s_ff1_i32_b64 s24, s[12:13]
	s_and_b64 s[12:13], s[22:23], s[12:13]
	v_add_u32_e32 v32, 0x4000, v32
	v_add_u32_e32 v122, v228, v32
	v_sub_u32_e32 v123, v32, v228
	s_and_b64 s[22:23], s[20:21], exec
	s_waitcnt vmcnt(0)
	ds_write2_b64 v122, v[116:117], v[40:41] offset0:128 offset1:132
	ds_write2_b64 v123, v[118:119], v[42:43] offset0:130 offset1:134
	s_movk_i32 s10, 0xc00
	s_cselect_b32 s84, s60, s24
	v_cndmask_b32_e64 v32, 0, 1, s[20:21]
	s_cselect_b32 s10, 0x1000, s10
	v_readfirstlane_b32 s24, v32
	v_mad_u64_u32 v[32:33], s[20:21], s84, v231, v[210:211]
	v_lshl_add_u64 v[36:37], v[32:33], 0, s[10:11]
	s_cselect_b32 s10, 0x200000, 0
	v_lshl_add_u64 v[32:33], v[212:213], 0, s[10:11]
	s_lshl_b64 s[20:21], s[84:85], 14
	v_lshl_add_u64 v[44:45], v[32:33], 0, s[20:21]
	global_load_dwordx4 v[32:35], v[36:37], off offset:16
	s_nop 0
	global_load_dwordx4 v[36:39], v[36:37], off
	s_nop 0
	global_load_dwordx4 v[40:43], v[44:45], off offset:16
	s_nop 0
	global_load_dwordx4 v[44:47], v[44:45], off
	v_mov_b32_e32 v116, 0x1200
	s_movk_i32 s10, 0x90
	v_mad_u32_u24 v239, v234, s10, v116
	v_lshlrev_b32_e32 v116, 8, v113
	v_mov_b32_e32 v117, v199
	v_mov_b32_e32 v115, v199
	v_lshl_add_u64 v[116:117], s[8:9], 0, v[116:117]
	v_lshl_add_u64 v[114:115], s[6:7], 0, v[114:115]
	v_lshl_add_u64 v[116:117], v[116:117], 0, v[198:199]
	s_mov_b64 s[4:5], 0x13e00000
	v_lshl_add_u64 v[116:117], v[116:117], 0, s[4:5]
	v_ashrrev_i32_e32 v113, 31, v112
	v_mad_i64_i32 v[118:119], s[4:5], v112, s96, v[114:115]
	s_mov_b64 s[6:7], 0x1402
	v_lshl_add_u64 v[214:215], v[118:119], 0, s[6:7]
	v_lshlrev_b64 v[118:119], 12, v[112:113]
	v_or_b32_e32 v112, 4, v112
	v_ashrrev_i32_e32 v113, 31, v112
	v_mad_i64_i32 v[114:115], s[4:5], v112, s96, v[114:115]
	v_lshlrev_b64 v[112:113], 12, v[112:113]
	v_lshl_add_u64 v[216:217], v[116:117], 0, v[118:119]
	v_lshl_add_u64 v[218:219], v[114:115], 0, s[6:7]
	v_lshl_add_u64 v[220:221], v[116:117], 0, v[112:113]
	s_mov_b64 s[20:21], -1
	v_mov_b32_e32 v198, 0
	s_mov_b32 s6, s84
	s_mov_b32 s84, s11
	s_waitcnt lgkmcnt(0)
	s_barrier
	s_branch .LBB0_339

; #define LAS __attribute__((address_space(3)))
; DI void attn_item(const Params& p, int item, LAS unsigned char* lds, int tid) {
;     ...
; #pragma unroll 1
;     for (;;) {
;         const LAS bf16_t* Kl = KV0 + buf * KVB; const LAS bf16_t* Vl = Kl + 64 * 136;
;         {
;             const bool sel0 = ((msk[0] >> kt) & 1ull) != 0ull, sel1 = ((msk[1] >> kt) & 1ull) != 0ull;
;             const float bias0 = (br || sel0) ? 0.f : -1e30f, bias1 = (br || sel1) ? 0.f : -1e30f;
;             const bool act0 = br || (__builtin_amdgcn_ballot_w64(sel0) != 0ull), act1 = br || (__builtin_amdgcn_ballot_w64(sel1) != 0ull);
;             const bool edge = (kt == tile) || (br && kt == tile - 8);
;             if (act0 && act1) attn_tile<3>(Kl, Vl, q, O, m, l, bias0, bias1, edge, br, kt, t0, tl, i16, quad);
;             else if (act0) attn_tile<1>(Kl, Vl, q, O, m, l, bias0, bias1, edge, br, kt, t0, tl, i16, quad);
;             else if (act1) attn_tile<2>(Kl, Vl, q, O, m, l, bias0, bias1, edge, br, kt, t0, tl, i16, quad);
;         }
.LBB0_339:
	s_cmpk_lt_u32 s33, 0x100
	s_cbranch_scc1 .Latt_nostag
	s_sleep 5

; #define LAS __attribute__((address_space(3)))
; template <int MASK> ...
;     f32x4 s[2][4];
; #pragma unroll
;     for (int np = 0; np < 2; ++np) {
;         bf16x8 kf[2][4];
; #pragma unroll
;         for (int n2 = 0; n2 < 2; ++n2)
; #pragma unroll
;             for (int kk = 0; kk < 4; ++kk) kf[n2][kk] = *(const LAS bf16x8*)(Kl + ((np * 2 + n2) * 16 + i16) * 136 + kk * 32 + quad * 8);
;         __builtin_amdgcn_sched_barrier(0);
; #pragma unroll
;         for (int n2 = 0; n2 < 2; ++n2) { s[0][np * 2 + n2] = (f32x4){bias0, bias0, bias0, bias0}; s[1][np * 2 + n2] = (f32x4){bias1, bias1, bias1, bias1}; }
; #pragma unroll
;         for (int kk = 0; kk < 4; ++kk)
; #pragma unroll
;             for (int n2 = 0; n2 < 2; ++n2) {
;                 if (MASK & 1) s[0][np * 2 + n2] = __builtin_amdgcn_mfma_f32_16x16x32_bf16(kf[n2][kk], q[0][kk], s[0][np * 2 + n2], 0, 0, 0);
;                 if (MASK & 2) s[1][np * 2 + n2] = __builtin_amdgcn_mfma_f32_16x16x32_bf16(kf[n2][kk], q[1][kk], s[1][np * 2 + n2], 0, 0, 0); }
;     }
;     u32x2 vlo0[8], vhi0[8];
; #pragma unroll
;     for (int dt = 0; dt < 8; ++dt) { const u32x4 vq = *(const LAS u32x4*)(Vl + (dt * 16 + i16) * 72 + quad * 8); vlo0[dt] = (u32x2){vq.x, vq.y}; vhi0[dt] = (u32x2){vq.z, vq.w}; }
;     __builtin_amdgcn_sched_barrier(0);
;     bf16x8 pa[2][2];
; #pragma unroll
;     for (int rt = 0; rt < 2; ++rt) {
;         if (!(MASK & (1 << rt))) continue;
;         const int t = t0 + rt * 4 + tl;
;         float tmx = -1e30f;
;         if (edge) {
; #pragma unroll
;             for (int nt = 0; nt < 4; ++nt)
; #pragma unroll
;                 for (int r = 0; r < 4; ++r) { const int key = kt * 64 + nt * 16 + quad * 4 + r;
;                     const bool ok = (key <= t) && (br ? (key > t - 512) : true);
;                     const float sv = ok ? s[rt][nt][r] : -1e30f; s[rt][nt][r] = sv; tmx = fmaxf(tmx, sv); }
;         } else {
; #pragma unroll
;             for (int nt = 0; nt < 4; ++nt) tmx = fmaxf(fmaxf(tmx, fmaxf(s[rt][nt][0], s[rt][nt][1])), fmaxf(s[rt][nt][2], s[rt][nt][3]));
;         }
;         tmx = xq_max(tmx);
.LBB0_343:
	s_mul_i32 s4, s11, 0x8c00
	s_or_b64 s[6:7], s[52:53], s[6:7]
	s_add_i32 s62, s4, 0
	s_xor_b64 s[4:5], s[52:53], -1
	v_cndmask_b32_e64 v112, v226, 0, s[6:7]
	s_or_b64 s[6:7], s[52:53], s[8:9]
	s_cmp_lg_u32 s54, s56
	v_cndmask_b32_e64 v116, v226, 0, s[6:7]
	s_cselect_b64 s[6:7], -1, 0
	s_cmp_lg_u32 s54, s57
	s_cselect_b64 s[8:9], -1, 0
	s_or_b64 s[4:5], s[4:5], s[8:9]
	s_and_b64 s[8:9], s[24:25], s[48:49]
	s_andn2_b64 vcc, exec, s[8:9]
	s_and_b64 s[8:9], s[6:7], s[4:5]
	s_cbranch_vccz .LBB0_363
	s_xor_b64 s[4:5], s[24:25], -1
	s_mov_b64 s[6:7], -1
	s_and_b64 vcc, exec, s[4:5]
	s_cbranch_vccz .LBB0_354
	v_mov_b64_e32 v[148:149], v[82:83]
	v_mov_b64_e32 v[144:145], v[86:87]
	v_mov_b64_e32 v[140:141], v[90:91]
	v_mov_b64_e32 v[136:137], v[94:95]
	v_mov_b64_e32 v[132:133], v[98:99]
	v_mov_b64_e32 v[128:129], v[102:103]
	v_mov_b64_e32 v[124:125], v[106:107]
	v_mov_b64_e32 v[120:121], v[110:111]
	s_andn2_b64 vcc, exec, s[48:49]
	v_mov_b64_e32 v[146:147], v[80:81]
	v_mov_b64_e32 v[142:143], v[84:85]
	v_mov_b64_e32 v[138:139], v[88:89]
	v_mov_b64_e32 v[134:135], v[92:93]
	v_mov_b64_e32 v[130:131], v[96:97]
	v_mov_b64_e32 v[126:127], v[100:101]
	v_mov_b64_e32 v[122:123], v[104:105]
	v_mov_b64_e32 v[118:119], v[108:109]
	v_mov_b32_e32 v248, v198
	v_mov_b32_e32 v247, v244
	s_cbranch_vccnz .LBB0_353
	v_add_u32_e32 v113, s62, v229
	v_add_u32_e32 v114, v113, v237
	ds_read_b128 v[120:123], v114
	ds_read_b128 v[124:127], v114 offset:64
	ds_read_b128 v[128:131], v114 offset:128
	ds_read_b128 v[132:135], v114 offset:192
	ds_read_b128 v[136:139], v114 offset:4352
	ds_read_b128 v[140:143], v114 offset:4416
	ds_read_b128 v[144:147], v114 offset:4480
	ds_read_b128 v[148:151], v114 offset:4544
	v_mov_b32_e32 v118, v116
	v_mov_b32_e32 v119, v116
	v_mov_b32_e32 v117, v116
	s_waitcnt lgkmcnt(7)
	s_nop 0
	v_mfma_f32_16x16x32_bf16 v[120:123], v[120:123], v[16:19], v[116:119]
	s_waitcnt lgkmcnt(3)
	v_mfma_f32_16x16x32_bf16 v[136:139], v[136:139], v[16:19], v[116:119]
	v_mfma_f32_16x16x32_bf16 v[120:123], v[124:127], v[24:27], v[120:123]
	s_waitcnt lgkmcnt(2)
	v_mfma_f32_16x16x32_bf16 v[124:127], v[140:143], v[24:27], v[136:139]
	v_mfma_f32_16x16x32_bf16 v[120:123], v[128:131], v[20:23], v[120:123]
	s_waitcnt lgkmcnt(1)
	v_mfma_f32_16x16x32_bf16 v[124:127], v[144:147], v[20:23], v[124:127]
	v_mfma_f32_16x16x32_bf16 v[158:161], v[132:135], v[28:31], v[120:123]
	s_waitcnt lgkmcnt(0)
	v_mfma_f32_16x16x32_bf16 v[142:145], v[148:151], v[28:31], v[124:127]
	s_nop 2
	ds_read_b128 v[120:123], v114 offset:8704
	s_nop 0
	ds_read_b128 v[124:127], v114 offset:8768
	ds_read_b128 v[128:131], v114 offset:8832
	ds_read_b128 v[132:135], v114 offset:8896
	ds_read_b128 v[136:139], v114 offset:13056
	ds_read_b128 v[146:149], v114 offset:13120
	ds_read_b128 v[150:153], v114 offset:13184
	ds_read_b128 v[154:157], v114 offset:13248
	s_waitcnt lgkmcnt(7)
	v_mfma_f32_16x16x32_bf16 v[120:123], v[120:123], v[16:19], v[116:119]
	v_add_u32_e32 v113, v113, v238
	s_waitcnt lgkmcnt(3)
	v_mfma_f32_16x16x32_bf16 v[136:139], v[136:139], v[16:19], v[116:119]
	v_mfma_f32_16x16x32_bf16 v[118:121], v[124:127], v[24:27], v[120:123]
	s_waitcnt lgkmcnt(2)
	v_mfma_f32_16x16x32_bf16 v[122:125], v[146:149], v[24:27], v[136:139]
	v_mfma_f32_16x16x32_bf16 v[118:121], v[128:131], v[20:23], v[118:121]
	s_waitcnt lgkmcnt(1)
	v_mfma_f32_16x16x32_bf16 v[122:125], v[150:153], v[20:23], v[122:125]
	v_mfma_f32_16x16x32_bf16 v[162:165], v[132:135], v[28:31], v[118:121]
	s_waitcnt lgkmcnt(0)
	v_mfma_f32_16x16x32_bf16 v[118:121], v[154:157], v[28:31], v[122:125]
	ds_read_b128 v[146:149], v113 offset:17408
	ds_read_b128 v[154:157], v113 offset:19712
	ds_read_b128 v[150:153], v113 offset:22016
	ds_read_b128 v[138:141], v113 offset:24320
	ds_read_b128 v[130:133], v113 offset:26624
	ds_read_b128 v[134:137], v113 offset:28928
	ds_read_b128 v[126:129], v113 offset:31232
	ds_read_b128 v[122:125], v113 offset:33536
	s_andn2_b64 vcc, exec, s[8:9]
	s_cbranch_vccnz .LBB0_348
	v_max_f32_e32 v113, v159, v159
	v_max_f32_e32 v114, v158, v158
	v_max_f32_e32 v113, v114, v113
	v_max_f32_e32 v114, v161, v161
	v_max_f32_e32 v115, v160, v160
	v_max_f32_e32 v114, v115, v114
	v_max3_f32 v113, v113, s97, v114
	v_max_f32_e32 v114, v143, v143
	v_max_f32_e32 v115, v142, v142
	v_max_f32_e32 v114, v115, v114
	v_max_f32_e32 v115, v145, v145
	v_max_f32_e32 v117, v144, v144
	v_max_f32_e32 v115, v117, v115
	v_max3_f32 v113, v113, v114, v115
	v_max_f32_e32 v114, v163, v163
	v_max_f32_e32 v115, v162, v162
	v_max_f32_e32 v114, v115, v114
	v_max_f32_e32 v115, v165, v165
	v_max_f32_e32 v117, v164, v164
	v_max_f32_e32 v115, v117, v115
	v_max3_f32 v113, v113, v114, v115
	v_max_f32_e32 v114, v119, v119
	v_max_f32_e32 v115, v118, v118
	v_max_f32_e32 v114, v115, v114
	v_max_f32_e32 v115, v121, v121
	v_max_f32_e32 v117, v120, v120
	v_max_f32_e32 v115, v117, v115
	v_max3_f32 v113, v113, v114, v115
	s_mov_b64 s[6:7], 0

; #define LAS __attribute__((address_space(3)))
; DI unsigned pk2(float lo, float hi) { f32x2 v = {lo, hi}; bf16v2 b = __builtin_convertvector(v, bf16v2); return __builtin_bit_cast(unsigned, b); }
; template <int MASK> ...
;     ...
;         const float mnew = (tmx > m[rt] + 8.f) ? tmx : m[rt];
;         const float corr = __builtin_amdgcn_exp2f(m[rt] - mnew);
;         float psum = 0.f;
; #pragma unroll
;         for (int nt = 0; nt < 4; ++nt)
; #pragma unroll
;             for (int r = 0; r < 4; ++r) { const float pe = __builtin_amdgcn_exp2f(s[rt][nt][r] - mnew); s[rt][nt][r] = pe; psum += pe; }
;         l[rt] = l[rt] * corr + psum; m[rt] = mnew;
;         if (__builtin_amdgcn_ballot_w64(corr != 1.f) != 0ull) {
; #pragma unroll
;             for (int dt = 0; dt < 8; ++dt) O[rt][dt] *= corr;
;         }
; #pragma unroll
;         for (int k2 = 0; k2 < 2; ++k2) {
;             u32x4 pw; pw.x = pk2(s[rt][2 * k2][0], s[rt][2 * k2][1]); pw.y = pk2(s[rt][2 * k2][2], s[rt][2 * k2][3]);
;             pw.z = pk2(s[rt][2 * k2 + 1][0], s[rt][2 * k2 + 1][1]); pw.w = pk2(s[rt][2 * k2 + 1][2], s[rt][2 * k2 + 1][3]);
;             pa[rt][k2] = __builtin_bit_cast(bf16x8, pw); }
;     }
; #pragma unroll
;     for (int dt = 0; dt < 8; ++dt) { const bf16x8 vv = __builtin_bit_cast(bf16x8, (u32x4){vlo0[dt].x, vlo0[dt].y, vhi0[dt].x, vhi0[dt].y});
;         if (MASK & 1) O[0][dt] = __builtin_amdgcn_mfma_f32_16x16x32_bf16(vv, pa[0][0], O[0][dt], 0, 0, 0);
;         if (MASK & 2) O[1][dt] = __builtin_amdgcn_mfma_f32_16x16x32_bf16(vv, pa[1][0], O[1][dt], 0, 0, 0); }
;     {
;         u32x2 vlo[8], vhi[8];
; #pragma unroll
;         for (int dt = 0; dt < 8; ++dt) { const u32x4 vq = *(const LAS u32x4*)(Vl + (dt * 16 + i16) * 72 + 32 + quad * 8); vlo[dt] = (u32x2){vq.x, vq.y}; vhi[dt] = (u32x2){vq.z, vq.w}; }
;         __builtin_amdgcn_sched_barrier(0);
; #pragma unroll
;         for (int dt = 0; dt < 8; ++dt) { const bf16x8 vv = __builtin_bit_cast(bf16x8, (u32x4){vlo[dt].x, vlo[dt].y, vhi[dt].x, vhi[dt].y});
;             if (MASK & 1) O[0][dt] = __builtin_amdgcn_mfma_f32_16x16x32_bf16(vv, pa[0][1], O[0][dt], 0, 0, 0);
;             if (MASK & 2) O[1][dt] = __builtin_amdgcn_mfma_f32_16x16x32_bf16(vv, pa[1][1], O[1][dt], 0, 0, 0); }
;     }
.LBB0_352:
	v_sub_f32_e32 v113, v158, v247
	v_exp_f32_e32 v113, v113
	v_sub_f32_e32 v115, v159, v247
	v_exp_f32_e32 v115, v115
	v_sub_f32_e32 v117, v160, v247
	v_exp_f32_e32 v117, v117
	v_sub_f32_e32 v159, v161, v247
	v_exp_f32_e32 v159, v159
	v_sub_f32_e32 v142, v142, v247
	v_add_f32_e32 v158, 0, v113
	v_exp_f32_e32 v160, v142
	v_sub_f32_e32 v142, v143, v247
	v_add_f32_e32 v158, v115, v158
	v_exp_f32_e32 v161, v142
	v_sub_f32_e32 v143, v144, v247
	v_add_f32_e32 v142, v117, v158
	v_exp_f32_e32 v158, v143
	v_sub_f32_e32 v143, v145, v247
	v_add_f32_e32 v142, v159, v142
	v_exp_f32_e32 v145, v143
	v_sub_f32_e32 v143, v162, v247
	v_add_f32_e32 v142, v160, v142
	v_exp_f32_e32 v162, v143
	v_sub_f32_e32 v143, v163, v247
	v_add_f32_e32 v142, v161, v142
	v_exp_f32_e32 v163, v143
	v_add_f32_e32 v142, v158, v142
	v_add_f32_e32 v142, v145, v142
	v_add_f32_e32 v142, v162, v142
	v_add_f32_e32 v224, v163, v142
	v_sub_f32_e32 v142, v164, v247
	v_exp_f32_e32 v225, v142
	v_sub_f32_e32 v142, v165, v247
	v_exp_f32_e32 v246, v142
	v_sub_f32_e32 v118, v118, v247
	v_cvt_pk_bf16_f32 v142, v113, v115
	v_cvt_pk_bf16_f32 v143, v117, v159
	v_exp_f32_e32 v113, v118
	v_sub_f32_e32 v117, v119, v247
	v_exp_f32_e32 v117, v117
	v_sub_f32_e32 v118, v120, v247
	v_cvt_pk_bf16_f32 v144, v160, v161
	v_cvt_pk_bf16_f32 v145, v158, v145
	v_add_f32_e32 v115, v225, v224
	v_exp_f32_e32 v161, v118
	v_sub_f32_e32 v158, v121, v247
	v_add_f32_e32 v115, v246, v115
	s_waitcnt lgkmcnt(4)
	v_mfma_f32_16x16x32_bf16 v[118:121], v[138:141], v[142:145], v[178:181]
	v_exp_f32_e32 v138, v158
	v_add_f32_e32 v115, v113, v115
	v_add_f32_e32 v115, v117, v115
	v_add_f32_e32 v115, v161, v115
	v_add_f32_e32 v248, v138, v115
	v_cvt_pk_bf16_f32 v160, v113, v117
	v_add3_u32 v113, s62, v238, v229
	v_mfma_f32_16x16x32_bf16 v[146:149], v[146:149], v[142:145], v[166:169]
	v_fmac_f32_e32 v248, v198, v114
	v_cvt_pk_bf16_f32 v158, v162, v163
	v_cvt_pk_bf16_f32 v161, v161, v138
	v_mfma_f32_16x16x32_bf16 v[154:157], v[154:157], v[142:145], v[170:173]
	v_add3_u32 v114, s62, v239, v229
	v_cvt_pk_bf16_f32 v159, v225, v246
	v_mfma_f32_16x16x32_bf16 v[150:153], v[150:153], v[142:145], v[174:177]
	s_waitcnt lgkmcnt(3)
	v_mfma_f32_16x16x32_bf16 v[130:133], v[130:133], v[142:145], v[182:185]
	s_waitcnt lgkmcnt(2)
	v_mfma_f32_16x16x32_bf16 v[162:165], v[134:137], v[142:145], v[190:193]
	s_waitcnt lgkmcnt(1)
	v_mfma_f32_16x16x32_bf16 v[166:169], v[126:129], v[142:145], v[194:197]
	ds_read_b128 v[126:129], v113 offset:19776
	ds_read_b128 v[134:137], v113 offset:24384
	ds_read_b128 v[170:173], v113 offset:26688
	ds_read_b128 v[174:177], v113 offset:28992
	ds_read_b128 v[138:141], v114 offset:17472
	ds_read_b128 v[178:181], v113 offset:31296
	ds_read_b128 v[182:185], v113 offset:17472
	ds_read_b128 v[190:193], v113 offset:33600
	s_waitcnt lgkmcnt(8)
	v_mfma_f32_16x16x32_bf16 v[186:189], v[122:125], v[142:145], v[186:189]
	s_waitcnt lgkmcnt(1)
	v_mfma_f32_16x16x32_bf16 v[146:149], v[182:185], v[158:161], v[146:149]
	v_mfma_f32_16x16x32_bf16 v[142:145], v[126:129], v[158:161], v[154:157]
	v_mfma_f32_16x16x32_bf16 v[138:141], v[138:141], v[158:161], v[150:153]
	v_mfma_f32_16x16x32_bf16 v[134:137], v[134:137], v[158:161], v[118:121]
	v_mfma_f32_16x16x32_bf16 v[130:133], v[170:173], v[158:161], v[130:133]
	v_mfma_f32_16x16x32_bf16 v[126:129], v[174:177], v[158:161], v[162:165]
	v_mfma_f32_16x16x32_bf16 v[122:125], v[178:181], v[158:161], v[166:169]
	s_waitcnt lgkmcnt(0)
	v_mfma_f32_16x16x32_bf16 v[118:121], v[190:193], v[158:161], v[186:189]

; #define LAS __attribute__((address_space(3)))
; template <int MASK> ...
;     f32x4 s[2][4];
; #pragma unroll
;     for (int np = 0; np < 2; ++np) {
;         bf16x8 kf[2][4];
; #pragma unroll
;         for (int n2 = 0; n2 < 2; ++n2)
; #pragma unroll
;             for (int kk = 0; kk < 4; ++kk) kf[n2][kk] = *(const LAS bf16x8*)(Kl + ((np * 2 + n2) * 16 + i16) * 136 + kk * 32 + quad * 8);
;         __builtin_amdgcn_sched_barrier(0);
; #pragma unroll
;         for (int n2 = 0; n2 < 2; ++n2) { s[0][np * 2 + n2] = (f32x4){bias0, bias0, bias0, bias0}; s[1][np * 2 + n2] = (f32x4){bias1, bias1, bias1, bias1}; }
; #pragma unroll
;         for (int kk = 0; kk < 4; ++kk)
; #pragma unroll
;             for (int n2 = 0; n2 < 2; ++n2) {
;                 if (MASK & 1) s[0][np * 2 + n2] = __builtin_amdgcn_mfma_f32_16x16x32_bf16(kf[n2][kk], q[0][kk], s[0][np * 2 + n2], 0, 0, 0);
;                 if (MASK & 2) s[1][np * 2 + n2] = __builtin_amdgcn_mfma_f32_16x16x32_bf16(kf[n2][kk], q[1][kk], s[1][np * 2 + n2], 0, 0, 0); }
;     }
;     u32x2 vlo0[8], vhi0[8];
; #pragma unroll
;     for (int dt = 0; dt < 8; ++dt) { const u32x4 vq = *(const LAS u32x4*)(Vl + (dt * 16 + i16) * 72 + quad * 8); vlo0[dt] = (u32x2){vq.x, vq.y}; vhi0[dt] = (u32x2){vq.z, vq.w}; }
;     __builtin_amdgcn_sched_barrier(0);
;     bf16x8 pa[2][2];
; #pragma unroll
;     for (int rt = 0; rt < 2; ++rt) {
;         if (!(MASK & (1 << rt))) continue;
;         const int t = t0 + rt * 4 + tl;
;         float tmx = -1e30f;
;         if (edge) {
; #pragma unroll
;             for (int nt = 0; nt < 4; ++nt)
; #pragma unroll
;                 for (int r = 0; r < 4; ++r) { const int key = kt * 64 + nt * 16 + quad * 4 + r;
;                     const bool ok = (key <= t) && (br ? (key > t - 512) : true);
;                     const float sv = ok ? s[rt][nt][r] : -1e30f; s[rt][nt][r] = sv; tmx = fmaxf(tmx, sv); }
;         } else {
; #pragma unroll
;             for (int nt = 0; nt < 4; ++nt) tmx = fmaxf(fmaxf(tmx, fmaxf(s[rt][nt][0], s[rt][nt][1])), fmaxf(s[rt][nt][2], s[rt][nt][3]));
;         }
;         tmx = xq_max(tmx);
.LBB0_354:
	v_mov_b64_e32 v[168:169], v[78:79]
	v_mov_b64_e32 v[172:173], v[74:75]
	v_mov_b64_e32 v[176:177], v[70:71]
	v_mov_b64_e32 v[180:181], v[62:63]
	v_mov_b64_e32 v[164:165], v[50:51]
	v_mov_b64_e32 v[160:161], v[54:55]
	v_mov_b64_e32 v[156:157], v[58:59]
	v_mov_b64_e32 v[152:153], v[66:67]
	s_andn2_b64 vcc, exec, s[6:7]
	v_mov_b64_e32 v[166:167], v[76:77]
	v_mov_b64_e32 v[170:171], v[72:73]
	v_mov_b64_e32 v[174:175], v[68:69]
	v_mov_b64_e32 v[178:179], v[60:61]
	v_mov_b64_e32 v[162:163], v[48:49]
	v_mov_b64_e32 v[158:159], v[52:53]
	v_mov_b64_e32 v[154:155], v[56:57]
	v_mov_b64_e32 v[150:151], v[64:65]
	v_mov_b32_e32 v249, v243
	v_mov_b32_e32 v246, v245
	s_cbranch_vccnz .LBB0_362
	v_add_u32_e32 v117, s62, v229
	v_add_u32_e32 v150, v117, v237
	ds_read_b128 v[118:121], v150
	ds_read_b128 v[122:125], v150 offset:64
	ds_read_b128 v[126:129], v150 offset:128
	ds_read_b128 v[130:133], v150 offset:192
	ds_read_b128 v[134:137], v150 offset:4352
	ds_read_b128 v[138:141], v150 offset:4416
	ds_read_b128 v[142:145], v150 offset:4480
	ds_read_b128 v[146:149], v150 offset:4544
	v_mov_b32_e32 v113, v112
	v_mov_b32_e32 v114, v112
	v_mov_b32_e32 v115, v112
	s_waitcnt lgkmcnt(7)
	s_nop 0
	v_mfma_f32_16x16x32_bf16 v[118:121], v[118:121], v[0:3], v[112:115]
	s_waitcnt lgkmcnt(3)
	v_mfma_f32_16x16x32_bf16 v[134:137], v[134:137], v[0:3], v[112:115]
	v_mfma_f32_16x16x32_bf16 v[118:121], v[122:125], v[8:11], v[118:121]
	s_waitcnt lgkmcnt(2)
	v_mfma_f32_16x16x32_bf16 v[122:125], v[138:141], v[8:11], v[134:137]
	v_mfma_f32_16x16x32_bf16 v[118:121], v[126:129], v[4:7], v[118:121]
	s_waitcnt lgkmcnt(1)
	v_mfma_f32_16x16x32_bf16 v[122:125], v[142:145], v[4:7], v[122:125]
	v_mfma_f32_16x16x32_bf16 v[158:161], v[130:133], v[12:15], v[118:121]
	s_waitcnt lgkmcnt(0)
	v_mfma_f32_16x16x32_bf16 v[142:145], v[146:149], v[12:15], v[122:125]
	s_nop 2
	ds_read_b128 v[118:121], v150 offset:8704
	s_nop 0
	ds_read_b128 v[122:125], v150 offset:8768
	ds_read_b128 v[126:129], v150 offset:8832
	ds_read_b128 v[130:133], v150 offset:8896
	ds_read_b128 v[134:137], v150 offset:13056
	ds_read_b128 v[138:141], v150 offset:13120
	ds_read_b128 v[146:149], v150 offset:13184
	ds_read_b128 v[150:153], v150 offset:13248
	s_waitcnt lgkmcnt(7)
	v_mfma_f32_16x16x32_bf16 v[118:121], v[118:121], v[0:3], v[112:115]
	s_waitcnt lgkmcnt(3)
	v_mfma_f32_16x16x32_bf16 v[134:137], v[134:137], v[0:3], v[112:115]
	v_mfma_f32_16x16x32_bf16 v[118:121], v[122:125], v[8:11], v[118:121]
	s_nop 1
	v_add_u32_e32 v113, v117, v238
	s_waitcnt lgkmcnt(2)
	v_mfma_f32_16x16x32_bf16 v[122:125], v[138:141], v[8:11], v[134:137]
	v_mfma_f32_16x16x32_bf16 v[118:121], v[126:129], v[4:7], v[118:121]
	s_waitcnt lgkmcnt(1)
	v_mfma_f32_16x16x32_bf16 v[122:125], v[146:149], v[4:7], v[122:125]
	v_mfma_f32_16x16x32_bf16 v[162:165], v[130:133], v[12:15], v[118:121]
	s_waitcnt lgkmcnt(0)
	v_mfma_f32_16x16x32_bf16 v[118:121], v[150:153], v[12:15], v[122:125]
	ds_read_b128 v[146:149], v113 offset:17408
	ds_read_b128 v[154:157], v113 offset:19712
	ds_read_b128 v[150:153], v113 offset:22016
	ds_read_b128 v[138:141], v113 offset:24320
	ds_read_b128 v[130:133], v113 offset:26624
	ds_read_b128 v[134:137], v113 offset:28928
	ds_read_b128 v[126:129], v113 offset:31232
	ds_read_b128 v[122:125], v113 offset:33536
	s_andn2_b64 vcc, exec, s[8:9]
	s_mov_b64 s[6:7], -1
	s_cbranch_vccnz .LBB0_357
	v_max_f32_e32 v113, v159, v159
	v_max_f32_e32 v114, v158, v158
	v_max_f32_e32 v113, v114, v113
	v_max_f32_e32 v114, v161, v161
	v_max_f32_e32 v115, v160, v160
	v_max_f32_e32 v114, v115, v114
	v_max3_f32 v113, v113, s97, v114
	v_max_f32_e32 v114, v143, v143
	v_max_f32_e32 v115, v142, v142
	v_max_f32_e32 v114, v115, v114
	v_max_f32_e32 v115, v145, v145
	v_max_f32_e32 v117, v144, v144
	v_max_f32_e32 v115, v117, v115
	v_max3_f32 v113, v113, v114, v115
	v_max_f32_e32 v114, v163, v163
	v_max_f32_e32 v115, v162, v162
	v_max_f32_e32 v114, v115, v114
	v_max_f32_e32 v115, v165, v165
	v_max_f32_e32 v117, v164, v164
	v_max_f32_e32 v115, v117, v115
	v_max3_f32 v113, v113, v114, v115
	v_max_f32_e32 v114, v119, v119
	v_max_f32_e32 v115, v118, v118
	v_max_f32_e32 v114, v115, v114
	v_max_f32_e32 v115, v121, v121
	v_max_f32_e32 v117, v120, v120
	v_max_f32_e32 v115, v117, v115
	v_max3_f32 v113, v113, v114, v115
	s_mov_b64 s[6:7], 0

; #define LAS __attribute__((address_space(3)))
; DI unsigned pk2(float lo, float hi) { f32x2 v = {lo, hi}; bf16v2 b = __builtin_convertvector(v, bf16v2); return __builtin_bit_cast(unsigned, b); }
; template <int MASK> ...
;     ...
;         const float mnew = (tmx > m[rt] + 8.f) ? tmx : m[rt];
;         const float corr = __builtin_amdgcn_exp2f(m[rt] - mnew);
;         float psum = 0.f;
; #pragma unroll
;         for (int nt = 0; nt < 4; ++nt)
; #pragma unroll
;             for (int r = 0; r < 4; ++r) { const float pe = __builtin_amdgcn_exp2f(s[rt][nt][r] - mnew); s[rt][nt][r] = pe; psum += pe; }
;         l[rt] = l[rt] * corr + psum; m[rt] = mnew;
;         if (__builtin_amdgcn_ballot_w64(corr != 1.f) != 0ull) {
; #pragma unroll
;             for (int dt = 0; dt < 8; ++dt) O[rt][dt] *= corr;
;         }
; #pragma unroll
;         for (int k2 = 0; k2 < 2; ++k2) {
;             u32x4 pw; pw.x = pk2(s[rt][2 * k2][0], s[rt][2 * k2][1]); pw.y = pk2(s[rt][2 * k2][2], s[rt][2 * k2][3]);
;             pw.z = pk2(s[rt][2 * k2 + 1][0], s[rt][2 * k2 + 1][1]); pw.w = pk2(s[rt][2 * k2 + 1][2], s[rt][2 * k2 + 1][3]);
;             pa[rt][k2] = __builtin_bit_cast(bf16x8, pw); }
;     }
; #pragma unroll
;     for (int dt = 0; dt < 8; ++dt) { const bf16x8 vv = __builtin_bit_cast(bf16x8, (u32x4){vlo0[dt].x, vlo0[dt].y, vhi0[dt].x, vhi0[dt].y});
;         if (MASK & 1) O[0][dt] = __builtin_amdgcn_mfma_f32_16x16x32_bf16(vv, pa[0][0], O[0][dt], 0, 0, 0);
;         if (MASK & 2) O[1][dt] = __builtin_amdgcn_mfma_f32_16x16x32_bf16(vv, pa[1][0], O[1][dt], 0, 0, 0); }
;     {
;         u32x2 vlo[8], vhi[8];
; #pragma unroll
;         for (int dt = 0; dt < 8; ++dt) { const u32x4 vq = *(const LAS u32x4*)(Vl + (dt * 16 + i16) * 72 + 32 + quad * 8); vlo[dt] = (u32x2){vq.x, vq.y}; vhi[dt] = (u32x2){vq.z, vq.w}; }
;         __builtin_amdgcn_sched_barrier(0);
; #pragma unroll
;         for (int dt = 0; dt < 8; ++dt) { const bf16x8 vv = __builtin_bit_cast(bf16x8, (u32x4){vlo[dt].x, vlo[dt].y, vhi[dt].x, vhi[dt].y});
;             if (MASK & 1) O[0][dt] = __builtin_amdgcn_mfma_f32_16x16x32_bf16(vv, pa[0][1], O[0][dt], 0, 0, 0);
;             if (MASK & 2) O[1][dt] = __builtin_amdgcn_mfma_f32_16x16x32_bf16(vv, pa[1][1], O[1][dt], 0, 0, 0); }
;     }
.LBB0_361:
	v_sub_f32_e32 v113, v158, v246
	v_exp_f32_e32 v113, v113
	v_sub_f32_e32 v115, v159, v246
	v_exp_f32_e32 v115, v115
	v_sub_f32_e32 v117, v160, v246
	v_exp_f32_e32 v117, v117
	v_sub_f32_e32 v159, v161, v246
	v_exp_f32_e32 v159, v159
	v_sub_f32_e32 v142, v142, v246
	v_add_f32_e32 v158, 0, v113
	v_exp_f32_e32 v160, v142
	v_sub_f32_e32 v142, v143, v246
	v_add_f32_e32 v158, v115, v158
	v_exp_f32_e32 v161, v142
	v_sub_f32_e32 v143, v144, v246
	v_add_f32_e32 v142, v117, v158
	v_exp_f32_e32 v158, v143
	v_sub_f32_e32 v143, v145, v246
	v_add_f32_e32 v142, v159, v142
	v_exp_f32_e32 v145, v143
	v_sub_f32_e32 v143, v162, v246
	v_add_f32_e32 v142, v160, v142
	v_exp_f32_e32 v162, v143
	v_sub_f32_e32 v143, v163, v246
	v_add_f32_e32 v142, v161, v142
	v_exp_f32_e32 v163, v143
	v_add_f32_e32 v142, v158, v142
	v_add_f32_e32 v142, v145, v142
	v_add_f32_e32 v142, v162, v142
	v_add_f32_e32 v224, v163, v142
	v_sub_f32_e32 v142, v164, v246
	v_exp_f32_e32 v164, v142
	v_sub_f32_e32 v142, v165, v246
	v_exp_f32_e32 v165, v142
	v_sub_f32_e32 v118, v118, v246
	v_cvt_pk_bf16_f32 v142, v113, v115
	v_cvt_pk_bf16_f32 v143, v117, v159
	v_exp_f32_e32 v113, v118
	v_sub_f32_e32 v117, v119, v246
	v_exp_f32_e32 v117, v117
	v_sub_f32_e32 v118, v120, v246
	v_cvt_pk_bf16_f32 v144, v160, v161
	v_cvt_pk_bf16_f32 v145, v158, v145
	v_add_f32_e32 v115, v164, v224
	v_exp_f32_e32 v158, v118
	v_sub_f32_e32 v159, v121, v246
	v_add_f32_e32 v115, v165, v115
	s_waitcnt lgkmcnt(4)
	v_mfma_f32_16x16x32_bf16 v[118:121], v[138:141], v[142:145], v[178:181]
	v_exp_f32_e32 v141, v159
	v_add_f32_e32 v115, v113, v115
	v_add_f32_e32 v115, v117, v115
	v_add_f32_e32 v115, v158, v115
	v_add_f32_e32 v249, v141, v115
	v_cvt_pk_bf16_f32 v140, v113, v117
	v_add3_u32 v113, s62, v238, v229
	v_mfma_f32_16x16x32_bf16 v[146:149], v[146:149], v[142:145], v[166:169]
	v_fmac_f32_e32 v249, v243, v114
	v_cvt_pk_bf16_f32 v138, v162, v163
	v_cvt_pk_bf16_f32 v139, v164, v165
	v_mfma_f32_16x16x32_bf16 v[150:153], v[150:153], v[142:145], v[174:177]
	v_cvt_pk_bf16_f32 v141, v158, v141
	v_add3_u32 v114, s62, v239, v229
	s_waitcnt lgkmcnt(3)
	v_mfma_f32_16x16x32_bf16 v[130:133], v[130:133], v[142:145], v[182:185]
	s_waitcnt lgkmcnt(2)
	v_mfma_f32_16x16x32_bf16 v[134:137], v[134:137], v[142:145], v[190:193]
	s_waitcnt lgkmcnt(1)
	v_mfma_f32_16x16x32_bf16 v[126:129], v[126:129], v[142:145], v[194:197]
	ds_read_b128 v[158:161], v113 offset:19776
	ds_read_b128 v[162:165], v113 offset:24384
	ds_read_b128 v[182:185], v113 offset:26688
	ds_read_b128 v[190:193], v113 offset:28992
	ds_read_b128 v[174:177], v114 offset:17472
	ds_read_b128 v[194:197], v113 offset:31296
	ds_read_b128 v[166:169], v113 offset:17472
	ds_read_b128 v[250:253], v113 offset:33600
	v_mfma_f32_16x16x32_bf16 v[154:157], v[154:157], v[142:145], v[170:173]
	s_waitcnt lgkmcnt(8)
	v_mfma_f32_16x16x32_bf16 v[122:125], v[122:125], v[142:145], v[186:189]
	s_waitcnt lgkmcnt(1)
	v_mfma_f32_16x16x32_bf16 v[166:169], v[166:169], v[138:141], v[146:149]
	v_mov_b64_e32 v[144:145], v[86:87]
	v_mov_b64_e32 v[142:143], v[84:85]
	v_mov_b32_e32 v248, v198
	v_mfma_f32_16x16x32_bf16 v[170:173], v[158:161], v[138:141], v[154:157]
	v_mov_b64_e32 v[148:149], v[82:83]
	v_mov_b64_e32 v[146:147], v[80:81]
	v_mov_b32_e32 v247, v244
	v_mfma_f32_16x16x32_bf16 v[174:177], v[174:177], v[138:141], v[150:153]
	v_mfma_f32_16x16x32_bf16 v[178:181], v[162:165], v[138:141], v[118:121]
	v_mfma_f32_16x16x32_bf16 v[162:165], v[182:185], v[138:141], v[130:133]
	s_nop 1
	v_mov_b64_e32 v[120:121], v[110:111]
	v_mov_b64_e32 v[118:119], v[108:109]
	v_mfma_f32_16x16x32_bf16 v[158:161], v[190:193], v[138:141], v[134:137]
	v_mov_b64_e32 v[132:133], v[98:99]
	v_mov_b64_e32 v[130:131], v[96:97]
	v_mfma_f32_16x16x32_bf16 v[154:157], v[194:197], v[138:141], v[126:129]
	v_mov_b64_e32 v[136:137], v[94:95]
	v_mov_b64_e32 v[134:135], v[92:93]
	s_waitcnt lgkmcnt(0)
	v_mfma_f32_16x16x32_bf16 v[150:153], v[250:253], v[138:141], v[122:125]
	v_mov_b64_e32 v[140:141], v[90:91]
	v_mov_b64_e32 v[128:129], v[102:103]
	v_mov_b64_e32 v[138:139], v[88:89]
	v_mov_b64_e32 v[124:125], v[106:107]
	v_mov_b64_e32 v[126:127], v[100:101]
	v_mov_b64_e32 v[122:123], v[104:105]

; #define LAS __attribute__((address_space(3)))
; template <int MASK> ...
;     ...
;     for (int np = 0; np < 2; ++np) {
;         bf16x8 kf[2][4];
; #pragma unroll
;         for (int n2 = 0; n2 < 2; ++n2)
; #pragma unroll
;             for (int kk = 0; kk < 4; ++kk) kf[n2][kk] = *(const LAS bf16x8*)(Kl + ((np * 2 + n2) * 16 + i16) * 136 + kk * 32 + quad * 8);
;         __builtin_amdgcn_sched_barrier(0);
; #pragma unroll
;         for (int n2 = 0; n2 < 2; ++n2) { s[0][np * 2 + n2] = (f32x4){bias0, bias0, bias0, bias0}; s[1][np * 2 + n2] = (f32x4){bias1, bias1, bias1, bias1}; }
; #pragma unroll
;         for (int kk = 0; kk < 4; ++kk)
; #pragma unroll
;             for (int n2 = 0; n2 < 2; ++n2) {
;                 if (MASK & 1) s[0][np * 2 + n2] = __builtin_amdgcn_mfma_f32_16x16x32_bf16(kf[n2][kk], q[0][kk], s[0][np * 2 + n2], 0, 0, 0);
;                 if (MASK & 2) s[1][np * 2 + n2] = __builtin_amdgcn_mfma_f32_16x16x32_bf16(kf[n2][kk], q[1][kk], s[1][np * 2 + n2], 0, 0, 0); }
;     }
;     u32x2 vlo0[8], vhi0[8];
; #pragma unroll
;     for (int dt = 0; dt < 8; ++dt) { const u32x4 vq = *(const LAS u32x4*)(Vl + (dt * 16 + i16) * 72 + quad * 8); vlo0[dt] = (u32x2){vq.x, vq.y}; vhi0[dt] = (u32x2){vq.z, vq.w}; }
;     __builtin_amdgcn_sched_barrier(0);
;     bf16x8 pa[2][2];
; #pragma unroll
;     for (int rt = 0; rt < 2; ++rt) {
;         if (!(MASK & (1 << rt))) continue;
;         const int t = t0 + rt * 4 + tl;
;         float tmx = -1e30f;
;         if (edge) {
; #pragma unroll
;             for (int nt = 0; nt < 4; ++nt)
; #pragma unroll
;                 for (int r = 0; r < 4; ++r) { const int key = kt * 64 + nt * 16 + quad * 4 + r;
;                     const bool ok = (key <= t) && (br ? (key > t - 512) : true);
;                     const float sv = ok ? s[rt][nt][r] : -1e30f; s[rt][nt][r] = sv; tmx = fmaxf(tmx, sv); }
;         } else {
; #pragma unroll
;             for (int nt = 0; nt < 4; ++nt) tmx = fmaxf(fmaxf(tmx, fmaxf(s[rt][nt][0], s[rt][nt][1])), fmaxf(s[rt][nt][2], s[rt][nt][3]));
.LBB0_363:
	s_andn2_b64 vcc, exec, s[22:23]
	s_cbranch_vccnz .LBB0_377
	v_add_u32_e32 v176, s62, v229
	v_add_u32_e32 v160, v176, v237
	ds_read_b128 v[120:123], v160
	ds_read_b128 v[124:127], v160 offset:64
	ds_read_b128 v[128:131], v160 offset:128
	ds_read_b128 v[132:135], v160 offset:192
	ds_read_b128 v[136:139], v160 offset:4352
	ds_read_b128 v[140:143], v160 offset:4416
	ds_read_b128 v[144:147], v160 offset:4480
	ds_read_b128 v[148:151], v160 offset:4544
	v_mov_b32_e32 v113, v112
	v_mov_b32_e32 v114, v112
	v_mov_b32_e32 v115, v112
	v_mov_b32_e32 v117, v116
	v_mov_b32_e32 v118, v116
	v_mov_b32_e32 v119, v116
	s_waitcnt lgkmcnt(7)
	v_mfma_f32_16x16x32_bf16 v[152:155], v[120:123], v[0:3], v[112:115]
	v_mfma_f32_16x16x32_bf16 v[120:123], v[120:123], v[16:19], v[116:119]
	s_waitcnt lgkmcnt(3)
	v_mfma_f32_16x16x32_bf16 v[156:159], v[136:139], v[0:3], v[112:115]
	v_mfma_f32_16x16x32_bf16 v[136:139], v[136:139], v[16:19], v[116:119]
	v_mfma_f32_16x16x32_bf16 v[152:155], v[124:127], v[8:11], v[152:155]
	v_mfma_f32_16x16x32_bf16 v[120:123], v[124:127], v[24:27], v[120:123]
	s_waitcnt lgkmcnt(2)
	v_mfma_f32_16x16x32_bf16 v[124:127], v[140:143], v[8:11], v[156:159]
	v_mfma_f32_16x16x32_bf16 v[136:139], v[140:143], v[24:27], v[136:139]
	v_mfma_f32_16x16x32_bf16 v[140:143], v[128:131], v[4:7], v[152:155]
	v_mfma_f32_16x16x32_bf16 v[120:123], v[128:131], v[20:23], v[120:123]
	s_waitcnt lgkmcnt(1)
	v_mfma_f32_16x16x32_bf16 v[124:127], v[144:147], v[4:7], v[124:127]
	v_mfma_f32_16x16x32_bf16 v[128:131], v[144:147], v[20:23], v[136:139]
	v_mfma_f32_16x16x32_bf16 v[152:155], v[132:135], v[12:15], v[140:143]
	v_mfma_f32_16x16x32_bf16 v[172:175], v[132:135], v[28:31], v[120:123]
	s_waitcnt lgkmcnt(0)
	v_mfma_f32_16x16x32_bf16 v[144:147], v[148:151], v[12:15], v[124:127]
	v_mfma_f32_16x16x32_bf16 v[164:167], v[148:151], v[28:31], v[128:131]
	ds_read_b128 v[120:123], v160 offset:8704
	s_nop 0
	ds_read_b128 v[124:127], v160 offset:8768
	ds_read_b128 v[128:131], v160 offset:8832
	ds_read_b128 v[132:135], v160 offset:8896
	ds_read_b128 v[136:139], v160 offset:13056
	ds_read_b128 v[140:143], v160 offset:13120
	ds_read_b128 v[148:151], v160 offset:13184
	ds_read_b128 v[160:163], v160 offset:13248
	s_waitcnt lgkmcnt(7)
	v_mfma_f32_16x16x32_bf16 v[156:159], v[120:123], v[0:3], v[112:115]
	s_waitcnt lgkmcnt(3)
	v_mfma_f32_16x16x32_bf16 v[112:115], v[136:139], v[0:3], v[112:115]
	v_mfma_f32_16x16x32_bf16 v[120:123], v[120:123], v[16:19], v[116:119]
	v_mfma_f32_16x16x32_bf16 v[116:119], v[136:139], v[16:19], v[116:119]
	s_waitcnt lgkmcnt(2)
	v_mfma_f32_16x16x32_bf16 v[112:115], v[140:143], v[8:11], v[112:115]
	v_mfma_f32_16x16x32_bf16 v[136:139], v[124:127], v[8:11], v[156:159]
	v_mfma_f32_16x16x32_bf16 v[120:123], v[124:127], v[24:27], v[120:123]
	v_mfma_f32_16x16x32_bf16 v[116:119], v[140:143], v[24:27], v[116:119]
	s_waitcnt lgkmcnt(1)
	v_mfma_f32_16x16x32_bf16 v[112:115], v[148:151], v[4:7], v[112:115]
	v_mfma_f32_16x16x32_bf16 v[124:127], v[128:131], v[4:7], v[136:139]
	v_mfma_f32_16x16x32_bf16 v[120:123], v[128:131], v[20:23], v[120:123]
	v_mfma_f32_16x16x32_bf16 v[116:119], v[148:151], v[20:23], v[116:119]
	s_waitcnt lgkmcnt(0)
	v_mfma_f32_16x16x32_bf16 v[148:151], v[160:163], v[12:15], v[112:115]
	s_nop 2
	v_add_u32_e32 v112, v176, v238
	v_mfma_f32_16x16x32_bf16 v[156:159], v[132:135], v[12:15], v[124:127]
	v_mfma_f32_16x16x32_bf16 v[168:171], v[132:135], v[28:31], v[120:123]
	v_mfma_f32_16x16x32_bf16 v[160:163], v[160:163], v[28:31], v[116:119]
	ds_read_b128 v[140:143], v112 offset:17408
	ds_read_b128 v[136:139], v112 offset:19712
	ds_read_b128 v[132:135], v112 offset:22016
	ds_read_b128 v[128:131], v112 offset:24320
	ds_read_b128 v[124:127], v112 offset:26624
	ds_read_b128 v[120:123], v112 offset:28928
	ds_read_b128 v[116:119], v112 offset:31232
	ds_read_b128 v[112:115], v112 offset:33536
	s_cmp_eq_u32 s84, 0
	v_cndmask_b32_e64 v176, 0, 1, s[8:9]
	s_cselect_b64 s[22:23], -1, 0
	v_cmp_ne_u32_e64 s[6:7], 1, v176
	s_andn2_b64 vcc, exec, s[8:9]
	s_mov_b64 s[8:9], -1
	s_cbranch_vccnz .LBB0_366
	v_max_f32_e32 v176, v153, v153
	v_max_f32_e32 v177, v152, v152
	v_max_f32_e32 v176, v177, v176
	v_max_f32_e32 v177, v155, v155
	v_max_f32_e32 v178, v154, v154
	v_max_f32_e32 v177, v178, v177
	v_max3_f32 v176, v176, s97, v177
	v_max_f32_e32 v177, v145, v145
	v_max_f32_e32 v178, v144, v144
	v_max_f32_e32 v177, v178, v177
	v_max_f32_e32 v178, v147, v147
	v_max_f32_e32 v179, v146, v146
	v_max_f32_e32 v178, v179, v178
	v_max3_f32 v176, v176, v177, v178
	v_max_f32_e32 v177, v157, v157
	v_max_f32_e32 v178, v156, v156
	v_max_f32_e32 v177, v178, v177
	v_max_f32_e32 v178, v159, v159
	v_max_f32_e32 v179, v158, v158
	v_max_f32_e32 v178, v179, v178
	v_max3_f32 v176, v176, v177, v178
	v_max_f32_e32 v177, v149, v149
	v_max_f32_e32 v178, v148, v148
	v_max_f32_e32 v177, v178, v177
	v_max_f32_e32 v178, v151, v151
	v_max_f32_e32 v179, v150, v150
	v_max_f32_e32 v178, v179, v178
	v_max3_f32 v176, v176, v177, v178
	s_mov_b64 s[8:9], 0

; #define LAS __attribute__((address_space(3)))
; DI unsigned pk2(float lo, float hi) { f32x2 v = {lo, hi}; bf16v2 b = __builtin_convertvector(v, bf16v2); return __builtin_bit_cast(unsigned, b); }
; template <int MASK> ...
;     ...
;         const float corr = __builtin_amdgcn_exp2f(m[rt] - mnew);
;         float psum = 0.f;
; #pragma unroll
;         for (int nt = 0; nt < 4; ++nt)
; #pragma unroll
;             for (int r = 0; r < 4; ++r) { const float pe = __builtin_amdgcn_exp2f(s[rt][nt][r] - mnew); s[rt][nt][r] = pe; psum += pe; }
;         l[rt] = l[rt] * corr + psum; m[rt] = mnew;
;         if (__builtin_amdgcn_ballot_w64(corr != 1.f) != 0ull) {
; #pragma unroll
;             for (int dt = 0; dt < 8; ++dt) O[rt][dt] *= corr;
;         }
; #pragma unroll
;         for (int k2 = 0; k2 < 2; ++k2) {
;             u32x4 pw; pw.x = pk2(s[rt][2 * k2][0], s[rt][2 * k2][1]); pw.y = pk2(s[rt][2 * k2][2], s[rt][2 * k2][3]);
;             pw.z = pk2(s[rt][2 * k2 + 1][0], s[rt][2 * k2 + 1][1]); pw.w = pk2(s[rt][2 * k2 + 1][2], s[rt][2 * k2 + 1][3]);
;             pa[rt][k2] = __builtin_bit_cast(bf16x8, pw); }
;     }
; #pragma unroll
;     for (int dt = 0; dt < 8; ++dt) { const bf16x8 vv = __builtin_bit_cast(bf16x8, (u32x4){vlo0[dt].x, vlo0[dt].y, vhi0[dt].x, vhi0[dt].y});
;         if (MASK & 1) O[0][dt] = __builtin_amdgcn_mfma_f32_16x16x32_bf16(vv, pa[0][0], O[0][dt], 0, 0, 0);
;         if (MASK & 2) O[1][dt] = __builtin_amdgcn_mfma_f32_16x16x32_bf16(vv, pa[1][0], O[1][dt], 0, 0, 0); }
;     {
;         u32x2 vlo[8], vhi[8];
; #pragma unroll
;         for (int dt = 0; dt < 8; ++dt) { const u32x4 vq = *(const LAS u32x4*)(Vl + (dt * 16 + i16) * 72 + 32 + quad * 8); vlo[dt] = (u32x2){vq.x, vq.y}; vhi[dt] = (u32x2){vq.z, vq.w}; }
;         __builtin_amdgcn_sched_barrier(0);
; #pragma unroll
;         for (int dt = 0; dt < 8; ++dt) { const bf16x8 vv = __builtin_bit_cast(bf16x8, (u32x4){vlo[dt].x, vlo[dt].y, vhi[dt].x, vhi[dt].y});
;             if (MASK & 1) O[0][dt] = __builtin_amdgcn_mfma_f32_16x16x32_bf16(vv, pa[0][1], O[0][dt], 0, 0, 0);
;             if (MASK & 2) O[1][dt] = __builtin_amdgcn_mfma_f32_16x16x32_bf16(vv, pa[1][1], O[1][dt], 0, 0, 0); }
;     }
.LBB0_376:
	v_sub_f32_e32 v172, v172, v247
	v_exp_f32_e32 v172, v172
	v_sub_f32_e32 v173, v173, v247
	v_exp_f32_e32 v173, v173
	v_sub_f32_e32 v174, v174, v247
	v_exp_f32_e32 v174, v174
	v_sub_f32_e32 v175, v175, v247
	v_exp_f32_e32 v175, v175
	v_sub_f32_e32 v164, v164, v247
	v_add_f32_e32 v177, 0, v172
	v_exp_f32_e32 v164, v164
	v_sub_f32_e32 v165, v165, v247
	v_add_f32_e32 v177, v173, v177
	v_exp_f32_e32 v165, v165
	v_sub_f32_e32 v166, v166, v247
	v_add_f32_e32 v177, v174, v177
	v_exp_f32_e32 v166, v166
	v_sub_f32_e32 v167, v167, v247
	v_add_f32_e32 v177, v175, v177
	v_exp_f32_e32 v167, v167
	v_sub_f32_e32 v168, v168, v247
	v_add_f32_e32 v177, v164, v177
	v_exp_f32_e32 v168, v168
	v_sub_f32_e32 v169, v169, v247
	v_add_f32_e32 v177, v165, v177
	v_exp_f32_e32 v169, v169
	v_sub_f32_e32 v170, v170, v247
	v_add_f32_e32 v177, v166, v177
	v_exp_f32_e32 v170, v170
	v_sub_f32_e32 v171, v171, v247
	v_add_f32_e32 v177, v167, v177
	v_exp_f32_e32 v171, v171
	v_sub_f32_e32 v160, v160, v247
	v_add_f32_e32 v177, v168, v177
	v_exp_f32_e32 v160, v160
	v_sub_f32_e32 v161, v161, v247
	v_add_f32_e32 v177, v169, v177
	v_exp_f32_e32 v161, v161
	v_sub_f32_e32 v162, v162, v247
	v_add_f32_e32 v177, v170, v177
	v_exp_f32_e32 v162, v162
	v_sub_f32_e32 v163, v163, v247
	v_add_f32_e32 v177, v171, v177
	v_exp_f32_e32 v163, v163
	v_add_f32_e32 v177, v160, v177
	v_add_f32_e32 v177, v161, v177
	v_add_f32_e32 v177, v162, v177
	v_sub_f32_e32 v152, v152, v246
	v_add_f32_e32 v248, v163, v177
	v_exp_f32_e32 v177, v152
	v_sub_f32_e32 v153, v153, v246
	v_fmac_f32_e32 v248, v198, v178
	v_exp_f32_e32 v178, v153
	v_sub_f32_e32 v153, v154, v246
	v_exp_f32_e32 v154, v153
	v_sub_f32_e32 v153, v155, v246
	v_exp_f32_e32 v155, v153
	v_sub_f32_e32 v144, v144, v246
	v_add_f32_e32 v152, 0, v177
	v_exp_f32_e32 v179, v144
	v_sub_f32_e32 v145, v145, v246
	v_add_f32_e32 v152, v178, v152
	v_exp_f32_e32 v180, v145
	v_sub_f32_e32 v145, v146, v246
	v_add_f32_e32 v152, v154, v152
	v_exp_f32_e32 v181, v145
	v_sub_f32_e32 v145, v147, v246
	v_add_f32_e32 v152, v155, v152
	v_exp_f32_e32 v147, v145
	v_sub_f32_e32 v145, v156, v246
	v_add_f32_e32 v144, v179, v152
	v_exp_f32_e32 v145, v145
	v_sub_f32_e32 v146, v157, v246
	v_add_f32_e32 v144, v180, v144
	v_exp_f32_e32 v146, v146
	v_sub_f32_e32 v152, v158, v246
	v_add_f32_e32 v144, v181, v144
	v_exp_f32_e32 v152, v152
	v_sub_f32_e32 v153, v159, v246
	v_add_f32_e32 v144, v147, v144
	v_exp_f32_e32 v153, v153
	v_sub_f32_e32 v148, v148, v246
	v_add_f32_e32 v144, v145, v144
	v_exp_f32_e32 v148, v148
	v_sub_f32_e32 v149, v149, v246
	v_add_f32_e32 v144, v146, v144
	v_exp_f32_e32 v149, v149
	v_sub_f32_e32 v150, v150, v246
	v_add_f32_e32 v144, v152, v144
	v_exp_f32_e32 v156, v150
	v_sub_f32_e32 v150, v151, v246
	v_add_f32_e32 v144, v153, v144
	v_exp_f32_e32 v157, v150
	v_add_f32_e32 v144, v148, v144
	v_add_f32_e32 v144, v149, v144
	v_add_f32_e32 v144, v156, v144
	v_add_f32_e32 v249, v157, v144
	v_cvt_pk_bf16_f32 v150, v145, v146
	v_cvt_pk_bf16_f32 v151, v152, v153
	v_cvt_pk_bf16_f32 v153, v156, v157
	v_cvt_pk_bf16_f32 v144, v177, v178
	v_cvt_pk_bf16_f32 v145, v154, v155
	v_cvt_pk_bf16_f32 v146, v179, v180
	v_cvt_pk_bf16_f32 v147, v181, v147
	v_cvt_pk_bf16_f32 v154, v172, v173
	v_cvt_pk_bf16_f32 v155, v174, v175
	v_cvt_pk_bf16_f32 v156, v164, v165
	v_cvt_pk_bf16_f32 v157, v166, v167
	s_waitcnt lgkmcnt(5)
	v_mfma_f32_16x16x32_bf16 v[68:71], v[132:135], v[144:147], v[68:71]
	v_fmac_f32_e32 v249, v243, v176
	v_cvt_pk_bf16_f32 v152, v148, v149
	v_cvt_pk_bf16_f32 v182, v168, v169
	v_mfma_f32_16x16x32_bf16 v[88:91], v[132:135], v[154:157], v[88:91]
	v_add3_u32 v132, s62, v238, v229
	v_cvt_pk_bf16_f32 v183, v170, v171
	v_cvt_pk_bf16_f32 v184, v160, v161
	s_waitcnt lgkmcnt(2)
	v_mfma_f32_16x16x32_bf16 v[52:55], v[120:123], v[144:147], v[52:55]
	v_cvt_pk_bf16_f32 v185, v162, v163
	v_mfma_f32_16x16x32_bf16 v[100:103], v[120:123], v[154:157], v[100:103]
	v_add3_u32 v120, s62, v239, v229
	v_mfma_f32_16x16x32_bf16 v[80:83], v[140:143], v[154:157], v[80:83]
	v_mfma_f32_16x16x32_bf16 v[84:87], v[136:139], v[154:157], v[84:87]
	v_mfma_f32_16x16x32_bf16 v[60:63], v[128:131], v[144:147], v[60:63]
	v_mfma_f32_16x16x32_bf16 v[92:95], v[128:131], v[154:157], v[92:95]
	v_mfma_f32_16x16x32_bf16 v[48:51], v[124:127], v[144:147], v[48:51]
	v_mfma_f32_16x16x32_bf16 v[96:99], v[124:127], v[154:157], v[96:99]
	s_waitcnt lgkmcnt(1)
	v_mfma_f32_16x16x32_bf16 v[56:59], v[116:119], v[144:147], v[56:59]
	v_mfma_f32_16x16x32_bf16 v[104:107], v[116:119], v[154:157], v[104:107]
	s_waitcnt lgkmcnt(0)
	v_mfma_f32_16x16x32_bf16 v[64:67], v[112:115], v[144:147], v[64:67]
	v_mfma_f32_16x16x32_bf16 v[108:111], v[112:115], v[154:157], v[108:111]
	ds_read_b128 v[112:115], v132 offset:17472
	ds_read_b128 v[116:119], v132 offset:19776
	ds_read_b128 v[120:123], v120 offset:17472
	ds_read_b128 v[124:127], v132 offset:24384
	ds_read_b128 v[128:131], v132 offset:26688
	ds_read_b128 v[154:157], v132 offset:28992
	ds_read_b128 v[186:189], v132 offset:31296
	ds_read_b128 v[190:193], v132 offset:33600
	v_mfma_f32_16x16x32_bf16 v[76:79], v[140:143], v[144:147], v[76:79]
	v_mfma_f32_16x16x32_bf16 v[72:75], v[136:139], v[144:147], v[72:75]
	s_waitcnt lgkmcnt(7)
	v_mfma_f32_16x16x32_bf16 v[166:169], v[112:115], v[150:153], v[76:79]
	v_mfma_f32_16x16x32_bf16 v[146:149], v[112:115], v[182:185], v[80:83]
	s_waitcnt lgkmcnt(6)
	v_mfma_f32_16x16x32_bf16 v[170:173], v[116:119], v[150:153], v[72:75]
	v_mfma_f32_16x16x32_bf16 v[142:145], v[116:119], v[182:185], v[84:87]
	s_waitcnt lgkmcnt(5)
	v_mfma_f32_16x16x32_bf16 v[174:177], v[120:123], v[150:153], v[68:71]
	v_mfma_f32_16x16x32_bf16 v[138:141], v[120:123], v[182:185], v[88:91]
	s_waitcnt lgkmcnt(4)
	v_mfma_f32_16x16x32_bf16 v[178:181], v[124:127], v[150:153], v[60:63]
	v_mfma_f32_16x16x32_bf16 v[134:137], v[124:127], v[182:185], v[92:95]
	s_waitcnt lgkmcnt(3)
	v_mfma_f32_16x16x32_bf16 v[162:165], v[128:131], v[150:153], v[48:51]
	v_mfma_f32_16x16x32_bf16 v[130:133], v[128:131], v[182:185], v[96:99]
	s_waitcnt lgkmcnt(2)
	v_mfma_f32_16x16x32_bf16 v[158:161], v[154:157], v[150:153], v[52:55]
	v_mfma_f32_16x16x32_bf16 v[126:129], v[154:157], v[182:185], v[100:103]
	s_waitcnt lgkmcnt(1)
	v_mfma_f32_16x16x32_bf16 v[154:157], v[186:189], v[150:153], v[56:59]
	v_mfma_f32_16x16x32_bf16 v[122:125], v[186:189], v[182:185], v[104:107]
	s_waitcnt lgkmcnt(0)
	v_mfma_f32_16x16x32_bf16 v[150:153], v[190:193], v[150:153], v[64:67]
	v_mfma_f32_16x16x32_bf16 v[118:121], v[190:193], v[182:185], v[108:111]

; #define LAS __attribute__((address_space(3)))
; #define ATT_PREFETCH(BR, KT) do { const bf16_t* ks_ = kb0 + (size_t)(KT) * 64 * NINP + ((BR) ? C_KW : C_KS); const bf16_t* vs_ = vb0 + (size_t)(BR) * 2 * 64 * 8192 + (size_t)(KT) * 8192; \
;         pk0 = *(const u32x4*)ks_; pk1 = *(const u32x4*)(ks_ + 8); pv0 = *(const u32x4*)vs_; pv1 = *(const u32x4*)(vs_ + 8); } while (0)
; DI void attn_item(const Params& p, int item, LAS unsigned char* lds, int tid) {
;     ...
;         {
;             LAS bf16_t* Kn = KV0 + (buf ^ 1) * KVB; LAS bf16_t* Vn = Kn + 64 * 136;
;             *(LAS u32x4*)(Kn + skey * 136 + sch * 16) = pk0; *(LAS u32x4*)(Kn + skey * 136 + sch * 16 + 8) = pk1;
;             { LAS bf16_t* vr_ = Vn + sdd * 72 + (sc4 >> 1) * 32 + (sc4 & 1) * 4;     *(LAS u32x2*)(vr_) = (u32x2){pv0.x, pv0.y}; *(LAS u32x2*)(vr_ + 8) = (u32x2){pv0.z, pv0.w}; *(LAS u32x2*)(vr_ + 16) = (u32x2){pv1.x, pv1.y}; *(LAS u32x2*)(vr_ + 24) = (u32x2){pv1.z, pv1.w}; }
;         }
;         br = nbr; kt = nkt; buf ^= 1;
;         nkt = kt + 1;
;         if (br == 0) { if (rem) { nkt = __builtin_ctzll(rem); rem &= rem - 1; } else { nbr = 1; nkt = kt_lo; } }
;         else if (nkt > kt_hi) has_next = false;
;         if (has_next) ATT_PREFETCH(nbr, nkt);
.LBB0_380:
	s_xor_b32 s11, s11, 1
	s_mul_i32 s4, s11, 0x8c00
	s_add_i32 s4, s4, 0
	v_add3_u32 v112, s4, v203, v208
	v_add_u32_e32 v113, v230, v112
	v_sub_u32_e32 v114, v112, v230
	s_waitcnt vmcnt(2)
	ds_write_b128 v113, v[36:39]
	ds_write_b128 v114, v[32:35] offset:16
	v_lshl_add_u32 v112, v209, 1, s4
	v_add3_u32 v112, v112, v235, v236
	v_add_u32_e32 v112, 0x4000, v112
	v_add_u32_e32 v113, v228, v112
	v_sub_u32_e32 v114, v112, v228
	s_cmp_lg_u32 s10, 0
	s_waitcnt vmcnt(0)
	ds_write2_b64 v113, v[44:45], v[40:41] offset0:128 offset1:132
	ds_write2_b64 v114, v[46:47], v[42:43] offset0:130 offset1:134
	s_cbranch_scc0 .LBB0_384
	s_add_i32 s6, s61, 1
	s_cmp_lt_i32 s61, s56
	s_cselect_b64 s[20:21], -1, 0
	s_mov_b32 s24, 1
	s_mov_b64 s[8:9], 0x800
	s_cbranch_execnz .LBB0_385

; DI void attn_item(const Params& p, int item, LAS unsigned char* lds, int tid) {
;     ...
;         __syncthreads();
;     }
;     ...
;     __syncthreads();
.LBB0_389:
	v_mov_b32_e32 v228, 0x41b17218
	v_mov_b32_e32 v229, 1
	v_mov_b32_e32 v230, 0x2600
	s_barrier
	s_branch .LBB0_334
